# RG-LRU passes: 1 - a*a via neg_lo / neg_hi modifiers of v_pk_fma_f32 instead of two v_xor sign flips (bit-identical, 128 VALU fewer per thread)
# speedup vs baseline: 1.0015x; 1.0014x over previous
; __device__ __forceinline__ f32x4 unpack4(u32x2 u) { return (f32x4){__uint_as_float(u.x << 16), __uint_as_float(u.x & 0xffff0000u), __uint_as_float(u.y << 16), __uint_as_float(u.y & 0xffff0000u)}; }
; template <int ph>
; __device__ __forceinline__ void run_phase(const Args& args, LAS unsigned char* lds, const int G, const int bx, const bool fin = true) {
;     ...
;             auto lru_ab = [](f32x4 gr, f32x4 gi, f32x4 xc, f32x4 sp, f32x4& a, f32x4& bb) {
;                 const f32x4 la = gr * sp; a = (f32x4){__expf(la[0]), __expf(la[1]), __expf(la[2]), __expf(la[3])};
;                 const f32x4 om = (f32x4){1.f, 1.f, 1.f, 1.f} - a * a;
;                 bb = (f32x4){sqrtf(fmaxf(om[0], 0.f)), sqrtf(fmaxf(om[1], 0.f)), sqrtf(fmaxf(om[2], 0.f)), sqrtf(fmaxf(om[3], 0.f))} * gi * xc; };
;     ...
; #pragma unroll 8
;                 for (int t = 0; t < 32; ++t) { const size_t o = base + (size_t)t * D;
;                     const u32x4 gr = *(const u32x4*)(GR + o), gi = *(const u32x4*)(GI + o), xc = *(const u32x4*)(XC + o);
;                     f32x4 a, bb;
;                     lru_ab(unpack4((u32x2){gr.x, gr.y}), unpack4((u32x2){gi.x, gi.y}), unpack4((u32x2){xc.x, xc.y}), sp0, a, bb); A0 = A0 * a; B0 = a * B0 + bb;
;                     lru_ab(unpack4((u32x2){gr.z, gr.w}), unpack4((u32x2){gi.z, gi.w}), unpack4((u32x2){xc.z, xc.w}), sp1, a, bb); A1 = A1 * a; B1 = a * B1 + bb; }
.LBB0_1061:
	v_lshl_add_u64 v[18:19], v[34:35], 0, s[24:25]
	v_add_co_u32_e32 v176, vcc, s46, v18
	s_nop 1
	v_addc_co_u32_e32 v177, vcc, 0, v19, vcc
	v_add_co_u32_e32 v178, vcc, s52, v18
	s_nop 1
	v_addc_co_u32_e32 v179, vcc, 0, v19, vcc
	v_add_co_u32_e32 v180, vcc, s47, v18
	s_nop 1
	v_addc_co_u32_e32 v181, vcc, 0, v19, vcc
	v_add_co_u32_e32 v182, vcc, s53, v18
	s_nop 1
	v_addc_co_u32_e32 v183, vcc, 0, v19, vcc
	v_add_co_u32_e32 v184, vcc, s48, v18
	s_nop 1
	v_addc_co_u32_e32 v185, vcc, 0, v19, vcc
	v_add_co_u32_e32 v186, vcc, s54, v18
	s_nop 1
	v_addc_co_u32_e32 v187, vcc, 0, v19, vcc
	v_add_co_u32_e32 v188, vcc, s55, v18
	s_nop 1
	v_addc_co_u32_e32 v189, vcc, 0, v19, vcc
	v_add_co_u32_e32 v190, vcc, s62, v18
	s_nop 1
	v_addc_co_u32_e32 v191, vcc, 0, v19, vcc
	v_add_co_u32_e32 v192, vcc, s56, v18
	s_nop 1
	v_addc_co_u32_e32 v193, vcc, 0, v19, vcc
	v_add_co_u32_e32 v194, vcc, s63, v18
	s_nop 1
	v_addc_co_u32_e32 v195, vcc, 0, v19, vcc
	v_add_co_u32_e32 v196, vcc, s57, v18
	s_nop 1
	v_addc_co_u32_e32 v197, vcc, 0, v19, vcc
	v_add_co_u32_e32 v198, vcc, s74, v18
	s_nop 1
	v_addc_co_u32_e32 v199, vcc, 0, v19, vcc
	global_load_dwordx4 v[80:83], v[178:179], off offset:-4096
	global_load_dwordx4 v[84:87], v[182:183], off offset:-4096
	global_load_dwordx4 v[88:91], v[186:187], off offset:-4096
	global_load_dwordx4 v[92:95], v[176:177], off offset:2048
	global_load_dwordx4 v[96:99], v[180:181], off offset:2048
	global_load_dwordx4 v[100:103], v[184:185], off offset:2048
	global_load_dwordx4 v[104:107], v[178:179], off
	global_load_dwordx4 v[108:111], v[182:183], off
	global_load_dwordx4 v[112:115], v[186:187], off
	global_load_dwordx4 v[116:119], v[178:179], off offset:2048
	global_load_dwordx4 v[120:123], v[182:183], off offset:2048
	global_load_dwordx4 v[124:127], v[186:187], off offset:2048
	global_load_dwordx4 v[128:131], v[190:191], off offset:-4096
	global_load_dwordx4 v[132:135], v[194:195], off offset:-4096
	global_load_dwordx4 v[136:139], v[198:199], off offset:-4096
	global_load_dwordx4 v[140:143], v[188:189], off offset:2048
	global_load_dwordx4 v[144:147], v[192:193], off offset:2048
	global_load_dwordx4 v[148:151], v[196:197], off offset:2048
	global_load_dwordx4 v[152:155], v[190:191], off
	global_load_dwordx4 v[156:159], v[194:195], off
	global_load_dwordx4 v[160:163], v[198:199], off
	global_load_dwordx4 v[164:167], v[190:191], off offset:2048
	global_load_dwordx4 v[168:171], v[194:195], off offset:2048
	global_load_dwordx4 v[172:175], v[198:199], off offset:2048
	s_add_u32 s24, s24, 0x4000
	s_nop 0
	s_addc_u32 s25, s25, 0
	s_nop 0
	s_cmp_eq_u32 s24, 0x10000
	s_nop 0
	s_nop 1
	s_nop 0
	s_waitcnt vmcnt(23)
	v_lshlrev_b32_e32 v70, 16, v80
	v_and_b32_e32 v71, 0xffff0000, v80
	v_pk_mul_f32 v[70:71], v[28:29], v[70:71]
	v_lshlrev_b32_e32 v40, 16, v81
	v_mul_f32_e32 v1, 0x3fb8aa3b, v70
	v_exp_f32_e32 v70, v1
	v_mul_f32_e32 v1, 0x3fb8aa3b, v71
	v_exp_f32_e32 v71, v1
	v_and_b32_e32 v41, 0xffff0000, v81
	v_pk_mul_f32 v[40:41], v[26:27], v[40:41]
	v_mul_f32_e32 v1, 0x3fb8aa3b, v40
	v_exp_f32_e32 v40, v1
	v_mul_f32_e32 v1, 0x3fb8aa3b, v41
	v_pk_fma_f32 v[78:79], v[70:71], v[70:71], 1.0 op_sel_hi:[1,1,0] neg_lo:[1,0,0] neg_hi:[1,0,0]
	v_exp_f32_e32 v41, v1
	v_max_f32_e32 v1, 0, v78
	v_pk_fma_f32 v[76:77], v[40:41], v[40:41], 1.0 op_sel_hi:[1,1,0] neg_lo:[1,0,0] neg_hi:[1,0,0]
	s_waitcnt vmcnt(22)
	v_lshlrev_b32_e32 v72, 16, v84
	v_and_b32_e32 v73, 0xffff0000, v84
	v_lshlrev_b32_e32 v44, 16, v85
	v_and_b32_e32 v45, 0xffff0000, v85
	s_waitcnt vmcnt(21)
	v_lshlrev_b32_e32 v74, 16, v88
	v_sqrt_f32_e32 v78, v1
	v_max_f32_e32 v1, 0, v79
	v_and_b32_e32 v75, 0xffff0000, v88
	v_lshlrev_b32_e32 v48, 16, v89
	v_and_b32_e32 v49, 0xffff0000, v89
	v_sqrt_f32_e32 v79, v1
	v_max_f32_e32 v1, 0, v76
	v_pk_mul_f32 v[72:73], v[78:79], v[72:73]
	v_sqrt_f32_e32 v76, v1
	v_max_f32_e32 v1, 0, v77
	v_sqrt_f32_e32 v77, v1
	s_nop 0
	v_pk_mul_f32 v[44:45], v[76:77], v[44:45]
	s_nop 0
	v_pk_mul_f32 v[44:45], v[44:45], v[48:49]
	v_pk_mul_f32 v[48:49], v[72:73], v[74:75]
	v_pk_mul_f32 v[74:75], v[8:9], v[40:41]
	v_pk_fma_f32 v[48:49], v[2:3], v[70:71], v[48:49]
	v_lshlrev_b32_e32 v2, 16, v82
	v_and_b32_e32 v3, 0xffff0000, v82
	v_pk_mul_f32 v[2:3], v[32:33], v[2:3]
	v_pk_fma_f32 v[40:41], v[4:5], v[40:41], v[44:45]
	v_mul_f32_e32 v1, 0x3fb8aa3b, v2
	v_exp_f32_e32 v2, v1
	v_mul_f32_e32 v1, 0x3fb8aa3b, v3
	v_exp_f32_e32 v3, v1
	v_lshlrev_b32_e32 v4, 16, v83
	v_and_b32_e32 v5, 0xffff0000, v83
	v_pk_mul_f32 v[4:5], v[30:31], v[4:5]
	v_lshlrev_b32_e32 v42, 16, v90
	v_and_b32_e32 v43, 0xffff0000, v90
	v_lshlrev_b32_e32 v44, 16, v91
	v_and_b32_e32 v45, 0xffff0000, v91
	v_mul_f32_e32 v1, 0x3fb8aa3b, v4
	v_exp_f32_e32 v4, v1
	v_mul_f32_e32 v1, 0x3fb8aa3b, v5
	v_pk_fma_f32 v[50:51], v[2:3], v[2:3], 1.0 op_sel_hi:[1,1,0] neg_lo:[1,0,0] neg_hi:[1,0,0]
	v_exp_f32_e32 v5, v1
	v_max_f32_e32 v1, 0, v50
	v_pk_mul_f32 v[72:73], v[6:7], v[70:71]
	v_lshlrev_b32_e32 v6, 16, v86
	v_and_b32_e32 v7, 0xffff0000, v86
	v_lshlrev_b32_e32 v8, 16, v87
	v_and_b32_e32 v9, 0xffff0000, v87
	v_pk_fma_f32 v[46:47], v[4:5], v[4:5], 1.0 op_sel_hi:[1,1,0] neg_lo:[1,0,0] neg_hi:[1,0,0]
	s_nop 0
	v_sqrt_f32_e32 v50, v1
	v_max_f32_e32 v1, 0, v51
	v_sqrt_f32_e32 v51, v1
	v_max_f32_e32 v1, 0, v46
	v_pk_mul_f32 v[6:7], v[50:51], v[6:7]
	v_pk_mul_f32 v[6:7], v[6:7], v[42:43]
	v_pk_mul_f32 v[42:43], v[10:11], v[2:3]
	v_pk_fma_f32 v[14:15], v[14:15], v[2:3], v[6:7]
	v_sqrt_f32_e32 v46, v1
	v_max_f32_e32 v1, 0, v47
	v_sqrt_f32_e32 v47, v1
	s_nop 0
	v_pk_mul_f32 v[8:9], v[46:47], v[8:9]
	s_nop 0
	v_pk_mul_f32 v[8:9], v[8:9], v[44:45]
	v_pk_mul_f32 v[44:45], v[12:13], v[4:5]
	v_pk_fma_f32 v[16:17], v[16:17], v[4:5], v[8:9]
	s_waitcnt vmcnt(20)
; __device__ __forceinline__ f32x4 unpack4(u32x2 u) { return (f32x4){__uint_as_float(u.x << 16), __uint_as_float(u.x & 0xffff0000u), __uint_as_float(u.y << 16), __uint_as_float(u.y & 0xffff0000u)}; }
; template <int ph>
; __device__ __forceinline__ void run_phase(const Args& args, LAS unsigned char* lds, const int G, const int bx, const bool fin = true) {
;     ...
;             auto lru_ab = [](f32x4 gr, f32x4 gi, f32x4 xc, f32x4 sp, f32x4& a, f32x4& bb) {
;                 const f32x4 la = gr * sp; a = (f32x4){__expf(la[0]), __expf(la[1]), __expf(la[2]), __expf(la[3])};
;                 const f32x4 om = (f32x4){1.f, 1.f, 1.f, 1.f} - a * a;
;                 bb = (f32x4){sqrtf(fmaxf(om[0], 0.f)), sqrtf(fmaxf(om[1], 0.f)), sqrtf(fmaxf(om[2], 0.f)), sqrtf(fmaxf(om[3], 0.f))} * gi * xc; };
;     ...
; #pragma unroll 8
;                 for (int t = 0; t < 32; ++t) { const size_t o = base + (size_t)t * D;
;                     const u32x4 gr = *(const u32x4*)(GR + o), gi = *(const u32x4*)(GI + o), xc = *(const u32x4*)(XC + o);
;                     f32x4 a, bb;
;                     lru_ab(unpack4((u32x2){gr.x, gr.y}), unpack4((u32x2){gi.x, gi.y}), unpack4((u32x2){xc.x, xc.y}), sp0, a, bb); A0 = A0 * a; B0 = a * B0 + bb;
;                     lru_ab(unpack4((u32x2){gr.z, gr.w}), unpack4((u32x2){gi.z, gi.w}), unpack4((u32x2){xc.z, xc.w}), sp1, a, bb); A1 = A1 * a; B1 = a * B1 + bb; }
	v_lshlrev_b32_e32 v46, 16, v92
	v_and_b32_e32 v47, 0xffff0000, v92
	v_pk_mul_f32 v[46:47], v[28:29], v[46:47]
	v_lshlrev_b32_e32 v2, 16, v93
	v_mul_f32_e32 v1, 0x3fb8aa3b, v46
	v_exp_f32_e32 v46, v1
	v_mul_f32_e32 v1, 0x3fb8aa3b, v47
	v_exp_f32_e32 v47, v1
	v_and_b32_e32 v3, 0xffff0000, v93
	v_pk_mul_f32 v[2:3], v[26:27], v[2:3]
	v_mul_f32_e32 v1, 0x3fb8aa3b, v2
	v_exp_f32_e32 v2, v1
	v_mul_f32_e32 v1, 0x3fb8aa3b, v3
	v_pk_fma_f32 v[66:67], v[46:47], v[46:47], 1.0 op_sel_hi:[1,1,0] neg_lo:[1,0,0] neg_hi:[1,0,0]
	v_exp_f32_e32 v3, v1
	v_max_f32_e32 v1, 0, v66
	v_pk_fma_f32 v[64:65], v[2:3], v[2:3], 1.0 op_sel_hi:[1,1,0] neg_lo:[1,0,0] neg_hi:[1,0,0]
	s_waitcnt vmcnt(19)
	v_lshlrev_b32_e32 v50, 16, v96
	v_and_b32_e32 v51, 0xffff0000, v96
	v_lshlrev_b32_e32 v6, 16, v97
	v_and_b32_e32 v7, 0xffff0000, v97
	s_waitcnt vmcnt(18)
	v_lshlrev_b32_e32 v62, 16, v100
	v_and_b32_e32 v63, 0xffff0000, v100
	v_sqrt_f32_e32 v66, v1
	v_max_f32_e32 v1, 0, v67
	v_lshlrev_b32_e32 v10, 16, v101
	v_and_b32_e32 v11, 0xffff0000, v101
	v_sqrt_f32_e32 v67, v1
	v_max_f32_e32 v1, 0, v64
	v_pk_mul_f32 v[50:51], v[66:67], v[50:51]
	v_pk_mul_f32 v[50:51], v[50:51], v[62:63]
	v_pk_mul_f32 v[62:63], v[74:75], v[2:3]
	v_sqrt_f32_e32 v64, v1
	v_max_f32_e32 v1, 0, v65
	v_sqrt_f32_e32 v65, v1
	s_nop 0
	v_pk_mul_f32 v[6:7], v[64:65], v[6:7]
	v_pk_mul_f32 v[64:65], v[72:73], v[46:47]
	v_pk_mul_f32 v[6:7], v[6:7], v[10:11]
	v_pk_fma_f32 v[46:47], v[48:49], v[46:47], v[50:51]
	v_pk_fma_f32 v[40:41], v[40:41], v[2:3], v[6:7]
	v_lshlrev_b32_e32 v2, 16, v94
	v_and_b32_e32 v3, 0xffff0000, v94
	v_pk_mul_f32 v[2:3], v[32:33], v[2:3]
	v_lshlrev_b32_e32 v4, 16, v95
	v_mul_f32_e32 v1, 0x3fb8aa3b, v2
	v_exp_f32_e32 v2, v1
	v_mul_f32_e32 v1, 0x3fb8aa3b, v3
	v_exp_f32_e32 v3, v1
	v_and_b32_e32 v5, 0xffff0000, v95
	v_pk_mul_f32 v[4:5], v[30:31], v[4:5]
	v_mul_f32_e32 v1, 0x3fb8aa3b, v4
	v_exp_f32_e32 v4, v1
	v_mul_f32_e32 v1, 0x3fb8aa3b, v5
	v_pk_fma_f32 v[50:51], v[2:3], v[2:3], 1.0 op_sel_hi:[1,1,0] neg_lo:[1,0,0] neg_hi:[1,0,0]
	v_exp_f32_e32 v5, v1
	v_max_f32_e32 v1, 0, v50
	v_pk_fma_f32 v[48:49], v[4:5], v[4:5], 1.0 op_sel_hi:[1,1,0] neg_lo:[1,0,0] neg_hi:[1,0,0]
	v_lshlrev_b32_e32 v6, 16, v98
	v_and_b32_e32 v7, 0xffff0000, v98
	v_lshlrev_b32_e32 v8, 16, v99
	v_and_b32_e32 v9, 0xffff0000, v99
	v_lshlrev_b32_e32 v10, 16, v102
	v_and_b32_e32 v11, 0xffff0000, v102
	v_sqrt_f32_e32 v50, v1
	v_max_f32_e32 v1, 0, v51
	v_lshlrev_b32_e32 v12, 16, v103
	v_and_b32_e32 v13, 0xffff0000, v103
	v_pk_mul_f32 v[44:45], v[44:45], v[4:5]
	v_pk_mul_f32 v[42:43], v[42:43], v[2:3]
	v_sqrt_f32_e32 v51, v1
	v_max_f32_e32 v1, 0, v48
	v_pk_mul_f32 v[6:7], v[50:51], v[6:7]
	v_pk_mul_f32 v[6:7], v[6:7], v[10:11]
	v_pk_fma_f32 v[14:15], v[14:15], v[2:3], v[6:7]
	v_sqrt_f32_e32 v48, v1
	v_max_f32_e32 v1, 0, v49
	v_sqrt_f32_e32 v49, v1
	s_nop 0
	v_pk_mul_f32 v[8:9], v[48:49], v[8:9]
	s_nop 0
	v_pk_mul_f32 v[8:9], v[8:9], v[12:13]
	s_nop 0
	v_pk_fma_f32 v[16:17], v[16:17], v[4:5], v[8:9]
	s_waitcnt vmcnt(17)
	v_lshlrev_b32_e32 v48, 16, v104
	v_and_b32_e32 v49, 0xffff0000, v104
	v_pk_mul_f32 v[48:49], v[28:29], v[48:49]
	v_lshlrev_b32_e32 v2, 16, v105
	v_mul_f32_e32 v1, 0x3fb8aa3b, v48
	v_exp_f32_e32 v48, v1
	v_mul_f32_e32 v1, 0x3fb8aa3b, v49
	v_exp_f32_e32 v49, v1
	v_and_b32_e32 v3, 0xffff0000, v105
	v_pk_mul_f32 v[2:3], v[26:27], v[2:3]
	v_mul_f32_e32 v1, 0x3fb8aa3b, v2
	v_exp_f32_e32 v2, v1
	v_mul_f32_e32 v1, 0x3fb8aa3b, v3
	v_pk_fma_f32 v[72:73], v[48:49], v[48:49], 1.0 op_sel_hi:[1,1,0] neg_lo:[1,0,0] neg_hi:[1,0,0]
	v_exp_f32_e32 v3, v1
	v_max_f32_e32 v1, 0, v72
	v_pk_fma_f32 v[70:71], v[2:3], v[2:3], 1.0 op_sel_hi:[1,1,0] neg_lo:[1,0,0] neg_hi:[1,0,0]
	s_waitcnt vmcnt(16)
	v_lshlrev_b32_e32 v50, 16, v108
	v_and_b32_e32 v51, 0xffff0000, v108
	v_lshlrev_b32_e32 v6, 16, v109
	v_and_b32_e32 v7, 0xffff0000, v109
	s_waitcnt vmcnt(15)
	v_lshlrev_b32_e32 v66, 16, v112
	v_and_b32_e32 v67, 0xffff0000, v112
	v_sqrt_f32_e32 v72, v1
	v_max_f32_e32 v1, 0, v73
	v_lshlrev_b32_e32 v10, 16, v113
	v_and_b32_e32 v11, 0xffff0000, v113
	v_pk_mul_f32 v[62:63], v[62:63], v[2:3]
	v_sqrt_f32_e32 v73, v1
	v_max_f32_e32 v1, 0, v70
	v_pk_mul_f32 v[50:51], v[72:73], v[50:51]
	v_sqrt_f32_e32 v70, v1
	v_max_f32_e32 v1, 0, v71
	v_sqrt_f32_e32 v71, v1
	s_nop 0
	v_pk_mul_f32 v[6:7], v[70:71], v[6:7]
	s_nop 0
	v_pk_mul_f32 v[6:7], v[6:7], v[10:11]
	v_pk_mul_f32 v[10:11], v[50:51], v[66:67]
	v_pk_fma_f32 v[40:41], v[40:41], v[2:3], v[6:7]
	v_lshlrev_b32_e32 v2, 16, v106
	v_and_b32_e32 v3, 0xffff0000, v106
	v_pk_mul_f32 v[2:3], v[32:33], v[2:3]
	v_lshlrev_b32_e32 v4, 16, v107
	v_mul_f32_e32 v1, 0x3fb8aa3b, v2
	v_exp_f32_e32 v2, v1
	v_mul_f32_e32 v1, 0x3fb8aa3b, v3
	v_exp_f32_e32 v3, v1
	v_and_b32_e32 v5, 0xffff0000, v107
	v_pk_mul_f32 v[4:5], v[30:31], v[4:5]
	v_pk_mul_f32 v[50:51], v[64:65], v[48:49]
	v_mul_f32_e32 v1, 0x3fb8aa3b, v4
	v_exp_f32_e32 v4, v1
	v_mul_f32_e32 v1, 0x3fb8aa3b, v5
	v_pk_fma_f32 v[64:65], v[2:3], v[2:3], 1.0 op_sel_hi:[1,1,0] neg_lo:[1,0,0] neg_hi:[1,0,0]
	v_exp_f32_e32 v5, v1
	v_max_f32_e32 v1, 0, v64
	v_pk_fma_f32 v[46:47], v[46:47], v[48:49], v[10:11]
	v_pk_fma_f32 v[48:49], v[4:5], v[4:5], 1.0 op_sel_hi:[1,1,0] neg_lo:[1,0,0] neg_hi:[1,0,0]
	v_lshlrev_b32_e32 v6, 16, v110
	v_and_b32_e32 v7, 0xffff0000, v110
	v_lshlrev_b32_e32 v8, 16, v111
	v_and_b32_e32 v9, 0xffff0000, v111
	v_lshlrev_b32_e32 v10, 16, v114
	v_sqrt_f32_e32 v64, v1
	v_max_f32_e32 v1, 0, v65
	v_and_b32_e32 v11, 0xffff0000, v114
	v_lshlrev_b32_e32 v12, 16, v115
	v_and_b32_e32 v13, 0xffff0000, v115
	v_pk_mul_f32 v[44:45], v[44:45], v[4:5]
	v_pk_mul_f32 v[42:43], v[42:43], v[2:3]
	v_sqrt_f32_e32 v65, v1
	v_max_f32_e32 v1, 0, v48
	v_pk_mul_f32 v[6:7], v[64:65], v[6:7]
	v_pk_mul_f32 v[6:7], v[6:7], v[10:11]
	v_sqrt_f32_e32 v48, v1
	v_max_f32_e32 v1, 0, v49
	v_sqrt_f32_e32 v49, v1
	s_nop 0
	v_pk_mul_f32 v[8:9], v[48:49], v[8:9]
	v_pk_fma_f32 v[48:49], v[14:15], v[2:3], v[6:7]
	v_pk_mul_f32 v[8:9], v[8:9], v[12:13]
	s_nop 0
	v_pk_fma_f32 v[8:9], v[16:17], v[4:5], v[8:9]
	s_nop 0
	s_waitcnt vmcnt(14)
; __device__ __forceinline__ f32x4 unpack4(u32x2 u) { return (f32x4){__uint_as_float(u.x << 16), __uint_as_float(u.x & 0xffff0000u), __uint_as_float(u.y << 16), __uint_as_float(u.y & 0xffff0000u)}; }
; template <int ph>
; __device__ __forceinline__ void run_phase(const Args& args, LAS unsigned char* lds, const int G, const int bx, const bool fin = true) {
;     ...
;             auto lru_ab = [](f32x4 gr, f32x4 gi, f32x4 xc, f32x4 sp, f32x4& a, f32x4& bb) {
;                 const f32x4 la = gr * sp; a = (f32x4){__expf(la[0]), __expf(la[1]), __expf(la[2]), __expf(la[3])};
;                 const f32x4 om = (f32x4){1.f, 1.f, 1.f, 1.f} - a * a;
;                 bb = (f32x4){sqrtf(fmaxf(om[0], 0.f)), sqrtf(fmaxf(om[1], 0.f)), sqrtf(fmaxf(om[2], 0.f)), sqrtf(fmaxf(om[3], 0.f))} * gi * xc; };
;     ...
; #pragma unroll 8
;                 for (int t = 0; t < 32; ++t) { const size_t o = base + (size_t)t * D;
;                     const u32x4 gr = *(const u32x4*)(GR + o), gi = *(const u32x4*)(GI + o), xc = *(const u32x4*)(XC + o);
;                     f32x4 a, bb;
;                     lru_ab(unpack4((u32x2){gr.x, gr.y}), unpack4((u32x2){gi.x, gi.y}), unpack4((u32x2){xc.x, xc.y}), sp0, a, bb); A0 = A0 * a; B0 = a * B0 + bb;
;                     lru_ab(unpack4((u32x2){gr.z, gr.w}), unpack4((u32x2){gi.z, gi.w}), unpack4((u32x2){xc.z, xc.w}), sp1, a, bb); A1 = A1 * a; B1 = a * B1 + bb; }
	v_lshlrev_b32_e32 v2, 16, v116
	v_and_b32_e32 v3, 0xffff0000, v116
	v_pk_mul_f32 v[2:3], v[28:29], v[2:3]
	s_waitcnt vmcnt(12)
	v_lshlrev_b32_e32 v16, 16, v124
	v_mul_f32_e32 v1, 0x3fb8aa3b, v2
	v_and_b32_e32 v17, 0xffff0000, v124
	v_exp_f32_e32 v36, v1
	v_mul_f32_e32 v1, 0x3fb8aa3b, v3
	v_lshlrev_b32_e32 v20, 16, v125
	v_and_b32_e32 v21, 0xffff0000, v125
	v_exp_f32_e32 v37, v1
	v_lshlrev_b32_e32 v4, 16, v117
	v_and_b32_e32 v5, 0xffff0000, v117
	v_pk_mul_f32 v[4:5], v[26:27], v[4:5]
	v_mul_f32_e32 v1, 0x3fb8aa3b, v4
	v_exp_f32_e32 v4, v1
	v_mul_f32_e32 v1, 0x3fb8aa3b, v5
	v_pk_fma_f32 v[64:65], v[36:37], v[36:37], 1.0 op_sel_hi:[1,1,0] neg_lo:[1,0,0] neg_hi:[1,0,0]
	v_exp_f32_e32 v5, v1
	v_max_f32_e32 v1, 0, v64
	v_pk_fma_f32 v[2:3], v[4:5], v[4:5], 1.0 op_sel_hi:[1,1,0] neg_lo:[1,0,0] neg_hi:[1,0,0]
	v_lshlrev_b32_e32 v10, 16, v120
	v_and_b32_e32 v11, 0xffff0000, v120
	v_lshlrev_b32_e32 v12, 16, v121
	v_and_b32_e32 v13, 0xffff0000, v121
	v_sqrt_f32_e32 v64, v1
	v_max_f32_e32 v1, 0, v65
	v_sqrt_f32_e32 v65, v1
	v_max_f32_e32 v1, 0, v2
	v_pk_mul_f32 v[10:11], v[64:65], v[10:11]
	v_sqrt_f32_e32 v2, v1
	v_max_f32_e32 v1, 0, v3
	v_sqrt_f32_e32 v3, v1
	s_nop 0
	v_pk_mul_f32 v[2:3], v[2:3], v[12:13]
	v_pk_mul_f32 v[12:13], v[10:11], v[16:17]
	v_pk_mul_f32 v[16:17], v[2:3], v[20:21]
	v_pk_mul_f32 v[2:3], v[62:63], v[4:5]
	v_pk_fma_f32 v[4:5], v[40:41], v[4:5], v[16:17]
	v_lshlrev_b32_e32 v16, 16, v118
	v_and_b32_e32 v17, 0xffff0000, v118
	v_pk_mul_f32 v[16:17], v[32:33], v[16:17]
	v_lshlrev_b32_e32 v6, 16, v119
	v_mul_f32_e32 v1, 0x3fb8aa3b, v16
	v_exp_f32_e32 v16, v1
	v_mul_f32_e32 v1, 0x3fb8aa3b, v17
	v_exp_f32_e32 v17, v1
	v_and_b32_e32 v7, 0xffff0000, v119
	v_pk_mul_f32 v[6:7], v[30:31], v[6:7]
	v_pk_fma_f32 v[12:13], v[46:47], v[36:37], v[12:13]
	v_mul_f32_e32 v1, 0x3fb8aa3b, v6
	v_exp_f32_e32 v40, v1
	v_mul_f32_e32 v1, 0x3fb8aa3b, v7
	v_pk_fma_f32 v[46:47], v[16:17], v[16:17], 1.0 op_sel_hi:[1,1,0] neg_lo:[1,0,0] neg_hi:[1,0,0]
	v_exp_f32_e32 v41, v1
	v_max_f32_e32 v1, 0, v46
	v_pk_mul_f32 v[10:11], v[50:51], v[36:37]
	v_pk_fma_f32 v[6:7], v[40:41], v[40:41], 1.0 op_sel_hi:[1,1,0] neg_lo:[1,0,0] neg_hi:[1,0,0]
	v_lshlrev_b32_e32 v20, 16, v122
	v_and_b32_e32 v21, 0xffff0000, v122
	v_lshlrev_b32_e32 v14, 16, v123
	v_and_b32_e32 v15, 0xffff0000, v123
	v_lshlrev_b32_e32 v36, 16, v126
	v_sqrt_f32_e32 v46, v1
	v_max_f32_e32 v1, 0, v47
	v_and_b32_e32 v37, 0xffff0000, v126
	v_lshlrev_b32_e32 v38, 16, v127
	v_and_b32_e32 v39, 0xffff0000, v127
	v_sqrt_f32_e32 v47, v1
	v_max_f32_e32 v1, 0, v6
	v_sqrt_f32_e32 v6, v1
	v_max_f32_e32 v1, 0, v7
	v_sqrt_f32_e32 v7, v1
	s_nop 0
	v_pk_mul_f32 v[6:7], v[6:7], v[14:15]
	v_pk_mul_f32 v[14:15], v[46:47], v[20:21]
	s_nop 0
	v_pk_mul_f32 v[20:21], v[14:15], v[36:37]
	v_pk_mul_f32 v[14:15], v[42:43], v[16:17]
	v_pk_fma_f32 v[16:17], v[48:49], v[16:17], v[20:21]
	v_pk_mul_f32 v[36:37], v[6:7], v[38:39]
	s_nop 0
	v_pk_fma_f32 v[8:9], v[8:9], v[40:41], v[36:37]
	s_nop 0
	v_pk_mul_f32 v[6:7], v[44:45], v[40:41]
	s_nop 0
	s_nop 1
	s_nop 0
	s_waitcnt vmcnt(11)
	v_lshlrev_b32_e32 v18, 16, v128
	v_and_b32_e32 v19, 0xffff0000, v128
	v_pk_mul_f32 v[18:19], v[28:29], v[18:19]
	v_lshlrev_b32_e32 v40, 16, v129
	v_mul_f32_e32 v1, 0x3fb8aa3b, v18
	v_exp_f32_e32 v74, v1
	v_mul_f32_e32 v1, 0x3fb8aa3b, v19
	v_exp_f32_e32 v75, v1
	v_and_b32_e32 v41, 0xffff0000, v129
	v_pk_mul_f32 v[40:41], v[26:27], v[40:41]
	v_mul_f32_e32 v1, 0x3fb8aa3b, v40
	v_exp_f32_e32 v40, v1
	v_mul_f32_e32 v1, 0x3fb8aa3b, v41
	v_pk_fma_f32 v[76:77], v[74:75], v[74:75], 1.0 op_sel_hi:[1,1,0] neg_lo:[1,0,0] neg_hi:[1,0,0]
	v_exp_f32_e32 v41, v1
	v_max_f32_e32 v1, 0, v76
	v_pk_fma_f32 v[18:19], v[40:41], v[40:41], 1.0 op_sel_hi:[1,1,0] neg_lo:[1,0,0] neg_hi:[1,0,0]
	s_waitcnt vmcnt(10)
	v_lshlrev_b32_e32 v48, 16, v132
	v_and_b32_e32 v49, 0xffff0000, v132
	v_lshlrev_b32_e32 v62, 16, v133
	v_and_b32_e32 v63, 0xffff0000, v133
	v_pk_mul_f32 v[10:11], v[10:11], v[74:75]
	s_waitcnt vmcnt(9)
	v_lshlrev_b32_e32 v66, 16, v136
	v_sqrt_f32_e32 v76, v1
	v_max_f32_e32 v1, 0, v77
	v_and_b32_e32 v67, 0xffff0000, v136
	v_lshlrev_b32_e32 v70, 16, v137
	v_and_b32_e32 v71, 0xffff0000, v137
	v_sqrt_f32_e32 v77, v1
	v_max_f32_e32 v1, 0, v18
	v_pk_mul_f32 v[48:49], v[76:77], v[48:49]
	v_pk_mul_f32 v[48:49], v[48:49], v[66:67]
	v_sqrt_f32_e32 v18, v1
	v_max_f32_e32 v1, 0, v19
	v_sqrt_f32_e32 v19, v1
	s_nop 0
	v_pk_mul_f32 v[18:19], v[18:19], v[62:63]
	s_nop 0
	v_pk_mul_f32 v[62:63], v[18:19], v[70:71]
	v_pk_mul_f32 v[18:19], v[2:3], v[40:41]
	v_pk_fma_f32 v[2:3], v[12:13], v[74:75], v[48:49]
	v_pk_fma_f32 v[12:13], v[4:5], v[40:41], v[62:63]
	v_lshlrev_b32_e32 v4, 16, v130
	v_and_b32_e32 v5, 0xffff0000, v130
	v_pk_mul_f32 v[4:5], v[32:33], v[4:5]
	v_lshlrev_b32_e32 v40, 16, v131
	v_mul_f32_e32 v1, 0x3fb8aa3b, v4
	v_exp_f32_e32 v66, v1
	v_mul_f32_e32 v1, 0x3fb8aa3b, v5
	v_exp_f32_e32 v67, v1
	v_and_b32_e32 v41, 0xffff0000, v131
	v_pk_mul_f32 v[40:41], v[30:31], v[40:41]
	v_mul_f32_e32 v1, 0x3fb8aa3b, v40
	v_exp_f32_e32 v40, v1
	v_mul_f32_e32 v1, 0x3fb8aa3b, v41
	v_pk_fma_f32 v[70:71], v[66:67], v[66:67], 1.0 op_sel_hi:[1,1,0] neg_lo:[1,0,0] neg_hi:[1,0,0]
	v_exp_f32_e32 v41, v1
	v_max_f32_e32 v1, 0, v70
	v_pk_fma_f32 v[4:5], v[40:41], v[40:41], 1.0 op_sel_hi:[1,1,0] neg_lo:[1,0,0] neg_hi:[1,0,0]
	v_lshlrev_b32_e32 v48, 16, v134
	v_and_b32_e32 v49, 0xffff0000, v134
	v_lshlrev_b32_e32 v50, 16, v135
	v_and_b32_e32 v51, 0xffff0000, v135
	v_lshlrev_b32_e32 v62, 16, v138
	v_and_b32_e32 v63, 0xffff0000, v138
	v_sqrt_f32_e32 v70, v1
	v_max_f32_e32 v1, 0, v71
	v_lshlrev_b32_e32 v64, 16, v139
	v_and_b32_e32 v65, 0xffff0000, v139
	v_sqrt_f32_e32 v71, v1
	v_max_f32_e32 v1, 0, v4
	v_pk_mul_f32 v[48:49], v[70:71], v[48:49]
	v_pk_mul_f32 v[48:49], v[48:49], v[62:63]
	v_sqrt_f32_e32 v4, v1
	v_max_f32_e32 v1, 0, v5
	v_sqrt_f32_e32 v5, v1
	s_nop 0
	v_pk_mul_f32 v[4:5], v[4:5], v[50:51]
	s_nop 0
	v_pk_mul_f32 v[50:51], v[4:5], v[64:65]
	v_pk_mul_f32 v[4:5], v[14:15], v[66:67]
	v_pk_mul_f32 v[14:15], v[6:7], v[40:41]
	v_pk_fma_f32 v[6:7], v[16:17], v[66:67], v[48:49]
	v_pk_fma_f32 v[8:9], v[8:9], v[40:41], v[50:51]
	s_nop 0
	s_waitcnt vmcnt(8)
; __device__ __forceinline__ f32x4 unpack4(u32x2 u) { return (f32x4){__uint_as_float(u.x << 16), __uint_as_float(u.x & 0xffff0000u), __uint_as_float(u.y << 16), __uint_as_float(u.y & 0xffff0000u)}; }
; template <int ph>
; __device__ __forceinline__ void run_phase(const Args& args, LAS unsigned char* lds, const int G, const int bx, const bool fin = true) {
;     ...
;             auto lru_ab = [](f32x4 gr, f32x4 gi, f32x4 xc, f32x4 sp, f32x4& a, f32x4& bb) {
;                 const f32x4 la = gr * sp; a = (f32x4){__expf(la[0]), __expf(la[1]), __expf(la[2]), __expf(la[3])};
;                 const f32x4 om = (f32x4){1.f, 1.f, 1.f, 1.f} - a * a;
;                 bb = (f32x4){sqrtf(fmaxf(om[0], 0.f)), sqrtf(fmaxf(om[1], 0.f)), sqrtf(fmaxf(om[2], 0.f)), sqrtf(fmaxf(om[3], 0.f))} * gi * xc; };
;     ...
; #pragma unroll 8
;                 for (int t = 0; t < 32; ++t) { const size_t o = base + (size_t)t * D;
;                     const u32x4 gr = *(const u32x4*)(GR + o), gi = *(const u32x4*)(GI + o), xc = *(const u32x4*)(XC + o);
;                     f32x4 a, bb;
;                     lru_ab(unpack4((u32x2){gr.x, gr.y}), unpack4((u32x2){gi.x, gi.y}), unpack4((u32x2){xc.x, xc.y}), sp0, a, bb); A0 = A0 * a; B0 = a * B0 + bb;
;                     lru_ab(unpack4((u32x2){gr.z, gr.w}), unpack4((u32x2){gi.z, gi.w}), unpack4((u32x2){xc.z, xc.w}), sp1, a, bb); A1 = A1 * a; B1 = a * B1 + bb; }
	v_lshlrev_b32_e32 v16, 16, v140
	v_and_b32_e32 v17, 0xffff0000, v140
	v_pk_mul_f32 v[16:17], v[28:29], v[16:17]
	v_lshlrev_b32_e32 v20, 16, v141
	v_mul_f32_e32 v1, 0x3fb8aa3b, v16
	v_exp_f32_e32 v66, v1
	v_mul_f32_e32 v1, 0x3fb8aa3b, v17
	v_exp_f32_e32 v67, v1
	v_and_b32_e32 v21, 0xffff0000, v141
	v_pk_mul_f32 v[20:21], v[26:27], v[20:21]
	v_mul_f32_e32 v1, 0x3fb8aa3b, v20
	v_exp_f32_e32 v20, v1
	v_mul_f32_e32 v1, 0x3fb8aa3b, v21
	v_pk_fma_f32 v[70:71], v[66:67], v[66:67], 1.0 op_sel_hi:[1,1,0] neg_lo:[1,0,0] neg_hi:[1,0,0]
	v_exp_f32_e32 v21, v1
	v_max_f32_e32 v1, 0, v70
	v_pk_fma_f32 v[16:17], v[20:21], v[20:21], 1.0 op_sel_hi:[1,1,0] neg_lo:[1,0,0] neg_hi:[1,0,0]
	s_waitcnt vmcnt(7)
	v_lshlrev_b32_e32 v40, 16, v144
	v_and_b32_e32 v41, 0xffff0000, v144
	v_lshlrev_b32_e32 v48, 16, v145
	v_and_b32_e32 v49, 0xffff0000, v145
	s_waitcnt vmcnt(6)
	v_lshlrev_b32_e32 v62, 16, v148
	v_and_b32_e32 v63, 0xffff0000, v148
	v_sqrt_f32_e32 v70, v1
	v_max_f32_e32 v1, 0, v71
	v_lshlrev_b32_e32 v36, 16, v149
	v_and_b32_e32 v37, 0xffff0000, v149
	v_sqrt_f32_e32 v71, v1
	v_max_f32_e32 v1, 0, v16
	v_pk_mul_f32 v[40:41], v[70:71], v[40:41]
	v_pk_mul_f32 v[40:41], v[40:41], v[62:63]
	v_sqrt_f32_e32 v16, v1
	v_max_f32_e32 v1, 0, v17
	v_sqrt_f32_e32 v17, v1
	s_nop 0
	v_pk_mul_f32 v[16:17], v[16:17], v[48:49]
	v_lshlrev_b32_e32 v48, 16, v150
	v_pk_mul_f32 v[36:37], v[16:17], v[36:37]
	v_pk_mul_f32 v[16:17], v[18:19], v[20:21]
	v_pk_mul_f32 v[18:19], v[10:11], v[66:67]
	v_pk_fma_f32 v[10:11], v[12:13], v[20:21], v[36:37]
	v_pk_fma_f32 v[20:21], v[2:3], v[66:67], v[40:41]
	v_lshlrev_b32_e32 v2, 16, v142
	v_and_b32_e32 v3, 0xffff0000, v142
	v_pk_mul_f32 v[2:3], v[32:33], v[2:3]
	v_lshlrev_b32_e32 v12, 16, v143
	v_mul_f32_e32 v1, 0x3fb8aa3b, v2
	v_exp_f32_e32 v2, v1
	v_mul_f32_e32 v1, 0x3fb8aa3b, v3
	v_exp_f32_e32 v3, v1
	v_and_b32_e32 v13, 0xffff0000, v143
	v_pk_mul_f32 v[12:13], v[30:31], v[12:13]
	v_mul_f32_e32 v1, 0x3fb8aa3b, v12
	v_exp_f32_e32 v50, v1
	v_mul_f32_e32 v1, 0x3fb8aa3b, v13
	v_pk_fma_f32 v[62:63], v[2:3], v[2:3], 1.0 op_sel_hi:[1,1,0] neg_lo:[1,0,0] neg_hi:[1,0,0]
	v_exp_f32_e32 v51, v1
	v_max_f32_e32 v1, 0, v62
	v_pk_fma_f32 v[12:13], v[50:51], v[50:51], 1.0 op_sel_hi:[1,1,0] neg_lo:[1,0,0] neg_hi:[1,0,0]
	v_lshlrev_b32_e32 v36, 16, v146
	v_and_b32_e32 v37, 0xffff0000, v146
	v_lshlrev_b32_e32 v40, 16, v147
	v_and_b32_e32 v41, 0xffff0000, v147
	v_and_b32_e32 v49, 0xffff0000, v150
	v_lshlrev_b32_e32 v38, 16, v151
	v_sqrt_f32_e32 v62, v1
	v_max_f32_e32 v1, 0, v63
	v_and_b32_e32 v39, 0xffff0000, v151
	v_sqrt_f32_e32 v63, v1
	v_max_f32_e32 v1, 0, v12
	v_pk_mul_f32 v[36:37], v[62:63], v[36:37]
	v_pk_mul_f32 v[36:37], v[36:37], v[48:49]
	v_pk_fma_f32 v[36:37], v[6:7], v[2:3], v[36:37]
	v_sqrt_f32_e32 v12, v1
	v_max_f32_e32 v1, 0, v13
	v_sqrt_f32_e32 v13, v1
	s_nop 0
	v_pk_mul_f32 v[12:13], v[12:13], v[40:41]
	s_nop 0
	v_pk_mul_f32 v[38:39], v[12:13], v[38:39]
	v_pk_mul_f32 v[12:13], v[14:15], v[50:51]
	v_pk_mul_f32 v[14:15], v[4:5], v[2:3]
	v_pk_fma_f32 v[8:9], v[8:9], v[50:51], v[38:39]
	s_waitcnt vmcnt(5)
	v_lshlrev_b32_e32 v6, 16, v152
	v_and_b32_e32 v7, 0xffff0000, v152
	v_pk_mul_f32 v[6:7], v[28:29], v[6:7]
	v_lshlrev_b32_e32 v2, 16, v153
	v_mul_f32_e32 v1, 0x3fb8aa3b, v6
	v_exp_f32_e32 v66, v1
	v_mul_f32_e32 v1, 0x3fb8aa3b, v7
	v_exp_f32_e32 v67, v1
	v_and_b32_e32 v3, 0xffff0000, v153
	v_pk_mul_f32 v[2:3], v[26:27], v[2:3]
	v_mul_f32_e32 v1, 0x3fb8aa3b, v2
	v_exp_f32_e32 v70, v1
	v_mul_f32_e32 v1, 0x3fb8aa3b, v3
	v_pk_fma_f32 v[6:7], v[66:67], v[66:67], 1.0 op_sel_hi:[1,1,0] neg_lo:[1,0,0] neg_hi:[1,0,0]
	v_exp_f32_e32 v71, v1
	v_max_f32_e32 v1, 0, v6
	v_pk_fma_f32 v[2:3], v[70:71], v[70:71], 1.0 op_sel_hi:[1,1,0] neg_lo:[1,0,0] neg_hi:[1,0,0]
	s_waitcnt vmcnt(4)
	v_lshlrev_b32_e32 v48, 16, v156
	v_and_b32_e32 v49, 0xffff0000, v156
	v_lshlrev_b32_e32 v38, 16, v157
	v_and_b32_e32 v39, 0xffff0000, v157
	s_waitcnt vmcnt(3)
	v_lshlrev_b32_e32 v50, 16, v160
	v_and_b32_e32 v51, 0xffff0000, v160
	v_sqrt_f32_e32 v6, v1
	v_max_f32_e32 v1, 0, v7
	v_lshlrev_b32_e32 v62, 16, v161
	v_and_b32_e32 v63, 0xffff0000, v161
	v_sqrt_f32_e32 v7, v1
	v_max_f32_e32 v1, 0, v2
	v_pk_mul_f32 v[6:7], v[6:7], v[48:49]
	v_pk_mul_f32 v[48:49], v[6:7], v[50:51]
	v_pk_mul_f32 v[6:7], v[16:17], v[70:71]
	v_lshlrev_b32_e32 v16, 16, v158
	v_and_b32_e32 v17, 0xffff0000, v158
	v_pk_fma_f32 v[48:49], v[20:21], v[66:67], v[48:49]
	v_lshlrev_b32_e32 v20, 16, v162
	v_and_b32_e32 v21, 0xffff0000, v162
	s_nop 0
	v_sqrt_f32_e32 v2, v1
	v_max_f32_e32 v1, 0, v3
	v_sqrt_f32_e32 v3, v1
	s_nop 0
	v_pk_mul_f32 v[2:3], v[2:3], v[38:39]
	s_nop 0
	v_pk_mul_f32 v[38:39], v[2:3], v[62:63]
	v_pk_mul_f32 v[2:3], v[18:19], v[66:67]
	v_pk_fma_f32 v[50:51], v[10:11], v[70:71], v[38:39]
	v_lshlrev_b32_e32 v10, 16, v154
	v_and_b32_e32 v11, 0xffff0000, v154
	v_pk_mul_f32 v[10:11], v[32:33], v[10:11]
	v_lshlrev_b32_e32 v4, 16, v155
	v_mul_f32_e32 v1, 0x3fb8aa3b, v10
	v_exp_f32_e32 v10, v1
	v_mul_f32_e32 v1, 0x3fb8aa3b, v11
	v_exp_f32_e32 v11, v1
	v_and_b32_e32 v5, 0xffff0000, v155
	v_pk_mul_f32 v[4:5], v[30:31], v[4:5]
	v_mul_f32_e32 v1, 0x3fb8aa3b, v4
	v_exp_f32_e32 v4, v1
	v_mul_f32_e32 v1, 0x3fb8aa3b, v5
	v_pk_fma_f32 v[62:63], v[10:11], v[10:11], 1.0 op_sel_hi:[1,1,0] neg_lo:[1,0,0] neg_hi:[1,0,0]
	v_exp_f32_e32 v5, v1
	v_max_f32_e32 v1, 0, v62
	v_lshlrev_b32_e32 v18, 16, v159
	v_and_b32_e32 v19, 0xffff0000, v159
	v_pk_fma_f32 v[40:41], v[4:5], v[4:5], 1.0 op_sel_hi:[1,1,0] neg_lo:[1,0,0] neg_hi:[1,0,0]
	v_lshlrev_b32_e32 v38, 16, v163
	v_and_b32_e32 v39, 0xffff0000, v163
	v_sqrt_f32_e32 v62, v1
	v_max_f32_e32 v1, 0, v63
	v_sqrt_f32_e32 v63, v1
	v_max_f32_e32 v1, 0, v40
	v_pk_mul_f32 v[16:17], v[62:63], v[16:17]
	v_pk_mul_f32 v[16:17], v[16:17], v[20:21]
	v_pk_mul_f32 v[20:21], v[14:15], v[10:11]
	v_pk_fma_f32 v[36:37], v[36:37], v[10:11], v[16:17]
	v_sqrt_f32_e32 v40, v1
	v_max_f32_e32 v1, 0, v41
	v_sqrt_f32_e32 v41, v1
	s_nop 0
	v_pk_mul_f32 v[18:19], v[40:41], v[18:19]
	s_nop 0
	v_pk_mul_f32 v[18:19], v[18:19], v[38:39]
	v_pk_mul_f32 v[38:39], v[12:13], v[4:5]
	v_pk_fma_f32 v[40:41], v[8:9], v[4:5], v[18:19]
	s_waitcnt vmcnt(2)
; __device__ __forceinline__ f32x4 unpack4(u32x2 u) { return (f32x4){__uint_as_float(u.x << 16), __uint_as_float(u.x & 0xffff0000u), __uint_as_float(u.y << 16), __uint_as_float(u.y & 0xffff0000u)}; }
; template <int ph>
; __device__ __forceinline__ void run_phase(const Args& args, LAS unsigned char* lds, const int G, const int bx, const bool fin = true) {
;     ...
; #pragma unroll 8
;                 for (int t = 0; t < 32; ++t) { const size_t o = base + (size_t)t * D;
;                     const u32x4 gr = *(const u32x4*)(GR + o), gi = *(const u32x4*)(GI + o), xc = *(const u32x4*)(XC + o);
;                     f32x4 a, bb;
;                     lru_ab(unpack4((u32x2){gr.x, gr.y}), unpack4((u32x2){gi.x, gi.y}), unpack4((u32x2){xc.x, xc.y}), sp0, a, bb); A0 = A0 * a; B0 = a * B0 + bb;
;                     lru_ab(unpack4((u32x2){gr.z, gr.w}), unpack4((u32x2){gi.z, gi.w}), unpack4((u32x2){xc.z, xc.w}), sp1, a, bb); A1 = A1 * a; B1 = a * B1 + bb; }
;                 sA[(seg * 8 + l8) * 2] = A0; sA[(seg * 8 + l8) * 2 + 1] = A1; sB[(seg * 8 + l8) * 2] = B0; sB[(seg * 8 + l8) * 2 + 1] = B1;
;                 __syncthreads();
;                 f32x4 h0 = (f32x4){0.f, 0.f, 0.f, 0.f}, h1 = h0;
;                 for (int s2 = 0; s2 < seg; ++s2) { h0 = sA[(s2 * 8 + l8) * 2] * h0 + sB[(s2 * 8 + l8) * 2]; h1 = sA[(s2 * 8 + l8) * 2 + 1] * h1 + sB[(s2 * 8 + l8) * 2 + 1]; }
	v_lshlrev_b32_e32 v4, 16, v164
	v_and_b32_e32 v5, 0xffff0000, v164
	v_pk_mul_f32 v[4:5], v[28:29], v[4:5]
	v_lshlrev_b32_e32 v16, 16, v165
	v_mul_f32_e32 v1, 0x3fb8aa3b, v4
	v_exp_f32_e32 v46, v1
	v_mul_f32_e32 v1, 0x3fb8aa3b, v5
	v_exp_f32_e32 v47, v1
	v_and_b32_e32 v17, 0xffff0000, v165
	v_pk_mul_f32 v[16:17], v[26:27], v[16:17]
	v_mul_f32_e32 v1, 0x3fb8aa3b, v16
	v_exp_f32_e32 v4, v1
	v_mul_f32_e32 v1, 0x3fb8aa3b, v17
	v_pk_fma_f32 v[62:63], v[46:47], v[46:47], 1.0 op_sel_hi:[1,1,0] neg_lo:[1,0,0] neg_hi:[1,0,0]
	v_exp_f32_e32 v5, v1
	v_max_f32_e32 v1, 0, v62
	v_pk_fma_f32 v[16:17], v[4:5], v[4:5], 1.0 op_sel_hi:[1,1,0] neg_lo:[1,0,0] neg_hi:[1,0,0]
	s_waitcnt vmcnt(1)
	v_lshlrev_b32_e32 v42, 16, v168
	v_and_b32_e32 v43, 0xffff0000, v168
	v_lshlrev_b32_e32 v12, 16, v169
	v_and_b32_e32 v13, 0xffff0000, v169
	s_waitcnt vmcnt(0)
	v_lshlrev_b32_e32 v44, 16, v172
	v_and_b32_e32 v45, 0xffff0000, v172
	v_sqrt_f32_e32 v62, v1
	v_max_f32_e32 v1, 0, v63
	v_lshlrev_b32_e32 v8, 16, v173
	v_and_b32_e32 v9, 0xffff0000, v173
	v_sqrt_f32_e32 v63, v1
	v_max_f32_e32 v1, 0, v16
	v_sqrt_f32_e32 v16, v1
	v_max_f32_e32 v1, 0, v17
	v_sqrt_f32_e32 v17, v1
	s_nop 0
	v_pk_mul_f32 v[12:13], v[16:17], v[12:13]
	v_pk_mul_f32 v[16:17], v[62:63], v[42:43]
	v_pk_mul_f32 v[12:13], v[12:13], v[8:9]
	v_pk_mul_f32 v[16:17], v[16:17], v[44:45]
	v_pk_mul_f32 v[8:9], v[6:7], v[4:5]
	v_pk_mul_f32 v[6:7], v[2:3], v[46:47]
	v_pk_fma_f32 v[2:3], v[48:49], v[46:47], v[16:17]
	v_lshlrev_b32_e32 v16, 16, v166
	v_and_b32_e32 v17, 0xffff0000, v166
	v_pk_fma_f32 v[4:5], v[50:51], v[4:5], v[12:13]
	v_lshlrev_b32_e32 v12, 16, v170
	v_and_b32_e32 v13, 0xffff0000, v170
	v_lshlrev_b32_e32 v42, 16, v171
	v_and_b32_e32 v43, 0xffff0000, v171
	v_pk_mul_f32 v[14:15], v[32:33], v[16:17]
	v_lshlrev_b32_e32 v44, 16, v167
	v_mul_f32_e32 v1, 0x3fb8aa3b, v14
	v_exp_f32_e32 v14, v1
	v_mul_f32_e32 v1, 0x3fb8aa3b, v15
	v_exp_f32_e32 v15, v1
	v_and_b32_e32 v45, 0xffff0000, v167
	v_pk_mul_f32 v[44:45], v[30:31], v[44:45]
	v_mul_f32_e32 v1, 0x3fb8aa3b, v44
	v_exp_f32_e32 v16, v1
	v_mul_f32_e32 v1, 0x3fb8aa3b, v45
	v_pk_fma_f32 v[46:47], v[14:15], v[14:15], 1.0 op_sel_hi:[1,1,0] neg_lo:[1,0,0] neg_hi:[1,0,0]
	v_exp_f32_e32 v17, v1
	v_max_f32_e32 v1, 0, v46
	v_pk_fma_f32 v[44:45], v[16:17], v[16:17], 1.0 op_sel_hi:[1,1,0] neg_lo:[1,0,0] neg_hi:[1,0,0]
	v_lshlrev_b32_e32 v18, 16, v174
	v_and_b32_e32 v19, 0xffff0000, v174
	v_lshlrev_b32_e32 v10, 16, v175
	v_and_b32_e32 v11, 0xffff0000, v175
	v_sqrt_f32_e32 v46, v1
	v_max_f32_e32 v1, 0, v47
	v_sqrt_f32_e32 v47, v1
	v_max_f32_e32 v1, 0, v44
	v_pk_mul_f32 v[12:13], v[46:47], v[12:13]
	v_pk_mul_f32 v[18:19], v[12:13], v[18:19]
	v_pk_mul_f32 v[12:13], v[38:39], v[16:17]
	v_sqrt_f32_e32 v44, v1
	v_max_f32_e32 v1, 0, v45
	v_sqrt_f32_e32 v45, v1
	s_nop 0
	v_pk_mul_f32 v[42:43], v[44:45], v[42:43]
	s_nop 0
	v_pk_mul_f32 v[42:43], v[42:43], v[10:11]
	v_pk_mul_f32 v[10:11], v[20:21], v[14:15]
	v_pk_fma_f32 v[16:17], v[40:41], v[16:17], v[42:43]
	v_pk_fma_f32 v[14:15], v[36:37], v[14:15], v[18:19]
	s_cbranch_scc0 .LBB0_1061
	ds_write_b128 v53, v[6:9]
	ds_write_b128 v53, v[10:13] offset:16
	ds_write_b128 v53, v[2:5] offset:16384
	ds_write_b128 v53, v[14:17] offset:16400
	v_mov_b32_e32 v9, 0
	v_mov_b32_e32 v8, 0
	v_mov_b32_e32 v7, 0
	v_mov_b32_e32 v6, 0
	v_mov_b32_e32 v5, 0
	v_mov_b32_e32 v4, 0
	v_mov_b32_e32 v3, 0
	v_mov_b32_e32 v2, 0
	s_waitcnt lgkmcnt(0)
	s_barrier
	s_and_saveexec_b64 s[0:1], s[2:3]
	s_cbranch_execz .LBB0_1072
	v_mov_b32_e32 v2, v0
	v_mov_b32_e32 v3, v0
	v_mov_b32_e32 v1, v0
	v_mov_b64_e32 v[8:9], v[2:3]
	v_mov_b64_e32 v[6:7], v[0:1]
	v_mov_b64_e32 v[4:5], v[2:3]
	v_mov_b32_e32 v10, 0
	v_mov_b64_e32 v[2:3], v[0:1]
	s_and_saveexec_b64 s[24:25], s[6:7]
	s_cbranch_execz .LBB0_1067
	v_mov_b32_e32 v2, 0
	s_mov_b32 s10, 0
	s_mov_b64 s[26:27], 0
	v_mov_b32_e32 v1, v56
	v_mov_b32_e32 v3, v2
	v_mov_b32_e32 v4, v2
	v_mov_b32_e32 v5, v2
	v_mov_b32_e32 v6, v2
	v_mov_b32_e32 v7, v2
	v_mov_b32_e32 v8, v2
	v_mov_b32_e32 v9, v2

; __device__ __forceinline__ f32x4 unpack4(u32x2 u) { return (f32x4){__uint_as_float(u.x << 16), __uint_as_float(u.x & 0xffff0000u), __uint_as_float(u.y << 16), __uint_as_float(u.y & 0xffff0000u)}; }
; __device__ __forceinline__ u32x2 pack4(f32x4 v) { u32x2 r; r.x = cvt_pk_bf16(v.x, v.y); r.y = cvt_pk_bf16(v.z, v.w); return r; }
; template <int ph>
; __device__ __forceinline__ void run_phase(const Args& args, LAS unsigned char* lds, const int G, const int bx, const bool fin = true) {
;     ...
;             auto lru_ab = [](f32x4 gr, f32x4 gi, f32x4 xc, f32x4 sp, f32x4& a, f32x4& bb) {
;                 const f32x4 la = gr * sp; a = (f32x4){__expf(la[0]), __expf(la[1]), __expf(la[2]), __expf(la[3])};
;                 const f32x4 om = (f32x4){1.f, 1.f, 1.f, 1.f} - a * a;
;                 bb = (f32x4){sqrtf(fmaxf(om[0], 0.f)), sqrtf(fmaxf(om[1], 0.f)), sqrtf(fmaxf(om[2], 0.f)), sqrtf(fmaxf(om[3], 0.f))} * gi * xc; };
;     ...
; #pragma unroll 8
;                 for (int t = 0; t < 32; ++t) { const size_t o = base + (size_t)t * D;
;                     const u32x4 gr = *(const u32x4*)(GR + o), gi = *(const u32x4*)(GI + o), xc = *(const u32x4*)(XC + o), gg = *(const u32x4*)(GG + o);
;                     f32x4 a, bb;
;                     lru_ab(unpack4((u32x2){gr.x, gr.y}), unpack4((u32x2){gi.x, gi.y}), unpack4((u32x2){xc.x, xc.y}), sp0, a, bb); h0 = a * h0 + bb;
;                     lru_ab(unpack4((u32x2){gr.z, gr.w}), unpack4((u32x2){gi.z, gi.w}), unpack4((u32x2){xc.z, xc.w}), sp1, a, bb); h1 = a * h1 + bb;
;                     const u32x2 w0 = pack4(h0 * unpack4((u32x2){gg.x, gg.y})), w1 = pack4(h1 * unpack4((u32x2){gg.z, gg.w}));
;                     *(u32x4*)(LO + o) = (u32x4){w0.x, w0.y, w1.x, w1.y}; }
.LBB0_1073:
	s_nop 0
	v_lshl_add_u64 v[10:11], v[34:35], 0, s[24:25]
	v_add_co_u32_e32 v200, vcc, 0x10700000, v10
	s_nop 1
	v_addc_co_u32_e32 v201, vcc, 0, v11, vcc
	v_add_co_u32_e32 v212, vcc, 0x16a00000, v10
	s_nop 1
	v_addc_co_u32_e32 v213, vcc, 0, v11, vcc
	v_add_co_u32_e32 v214, vcc, 0x7d80000, v10
	s_nop 1
	v_addc_co_u32_e32 v215, vcc, 0, v11, vcc
	v_add_co_u32_e32 v216, vcc, 0x12800000, v10
	s_nop 1
	v_addc_co_u32_e32 v217, vcc, 0, v11, vcc
	v_add_co_u32_e32 v218, vcc, s52, v10
	s_nop 1
	v_addc_co_u32_e32 v219, vcc, 0, v11, vcc
	v_add_co_u32_e32 v220, vcc, s55, v10
	s_nop 1
	v_addc_co_u32_e32 v221, vcc, 0, v11, vcc
	v_add_co_u32_e32 v222, vcc, s53, v10
	s_nop 1
	v_addc_co_u32_e32 v223, vcc, 0, v11, vcc
	v_add_co_u32_e32 v224, vcc, s56, v10
	s_nop 1
	v_addc_co_u32_e32 v225, vcc, 0, v11, vcc
	v_add_co_u32_e32 v226, vcc, s54, v10
	s_nop 1
	v_addc_co_u32_e32 v227, vcc, 0, v11, vcc
	v_add_co_u32_e32 v230, vcc, s57, v10
	s_nop 1
	v_addc_co_u32_e32 v231, vcc, 0, v11, vcc
	v_add_co_u32_e32 v232, vcc, s75, v10
	s_nop 1
	v_addc_co_u32_e32 v233, vcc, 0, v11, vcc
	v_add_co_u32_e32 v234, vcc, s76, v10
	s_nop 1
	v_addc_co_u32_e32 v235, vcc, 0, v11, vcc
	v_add_co_u32_e32 v236, vcc, s62, v10
	s_nop 1
	v_addc_co_u32_e32 v237, vcc, 0, v11, vcc
	v_add_co_u32_e32 v238, vcc, s63, v10
	s_nop 1
	v_addc_co_u32_e32 v239, vcc, 0, v11, vcc
	v_add_co_u32_e32 v240, vcc, s74, v10
	s_nop 1
	v_addc_co_u32_e32 v241, vcc, 0, v11, vcc
	v_add_co_u32_e32 v242, vcc, s77, v10
	s_nop 1
	v_addc_co_u32_e32 v243, vcc, 0, v11, vcc
	global_load_dwordx4 v[80:83], v[200:201], off
	global_load_dwordx4 v[84:87], v[212:213], off
	global_load_dwordx4 v[88:91], v[214:215], off
	global_load_dwordx4 v[92:95], v[216:217], off
	global_load_dwordx4 v[96:99], v[200:201], off offset:2048
	global_load_dwordx4 v[100:103], v[212:213], off offset:2048
	global_load_dwordx4 v[104:107], v[214:215], off offset:2048
	global_load_dwordx4 v[108:111], v[216:217], off offset:2048
	global_load_dwordx4 v[112:115], v[220:221], off offset:-4096
	global_load_dwordx4 v[116:119], v[224:225], off offset:-4096
	global_load_dwordx4 v[120:123], v[230:231], off offset:-4096
	global_load_dwordx4 v[124:127], v[234:235], off offset:-4096
	global_load_dwordx4 v[128:131], v[218:219], off offset:2048
	global_load_dwordx4 v[132:135], v[222:223], off offset:2048
	global_load_dwordx4 v[136:139], v[226:227], off offset:2048
	global_load_dwordx4 v[140:143], v[232:233], off offset:2048
	global_load_dwordx4 v[144:147], v[220:221], off
	global_load_dwordx4 v[148:151], v[224:225], off
	global_load_dwordx4 v[152:155], v[230:231], off
	global_load_dwordx4 v[156:159], v[234:235], off
	global_load_dwordx4 v[160:163], v[220:221], off offset:2048
	global_load_dwordx4 v[164:167], v[224:225], off offset:2048
	global_load_dwordx4 v[168:171], v[230:231], off offset:2048
	global_load_dwordx4 v[172:175], v[234:235], off offset:2048
	global_load_dwordx4 v[176:179], v[236:237], off
	global_load_dwordx4 v[180:183], v[238:239], off
	global_load_dwordx4 v[184:187], v[240:241], off
	global_load_dwordx4 v[188:191], v[242:243], off
	global_load_dwordx4 v[192:195], v[236:237], off offset:2048
	global_load_dwordx4 v[196:199], v[238:239], off offset:2048
	global_load_dwordx4 v[204:207], v[240:241], off offset:2048
	global_load_dwordx4 v[208:211], v[242:243], off offset:2048
	s_add_u32 s24, s24, 0x4000
	s_nop 0
	s_addc_u32 s25, s25, 0
	s_nop 0
	s_nop 0
	s_cmp_eq_u32 s24, 0x10000
	s_nop 0
	s_waitcnt vmcnt(31)
	v_lshlrev_b32_e32 v50, 16, v80
	v_and_b32_e32 v51, 0xffff0000, v80
	v_pk_mul_f32 v[50:51], v[28:29], v[50:51]
	v_lshlrev_b32_e32 v14, 16, v81
	v_mul_f32_e32 v1, 0x3fb8aa3b, v50
	v_exp_f32_e32 v50, v1
	v_mul_f32_e32 v1, 0x3fb8aa3b, v51
	v_exp_f32_e32 v51, v1
	v_and_b32_e32 v15, 0xffff0000, v81
	v_pk_mul_f32 v[14:15], v[26:27], v[14:15]
	v_mul_f32_e32 v1, 0x3fb8aa3b, v14
	v_exp_f32_e32 v14, v1
	v_mul_f32_e32 v1, 0x3fb8aa3b, v15
	v_pk_fma_f32 v[70:71], v[50:51], v[50:51], 1.0 op_sel_hi:[1,1,0] neg_lo:[1,0,0] neg_hi:[1,0,0]
	v_exp_f32_e32 v15, v1
	v_max_f32_e32 v1, 0, v70
	v_pk_fma_f32 v[66:67], v[14:15], v[14:15], 1.0 op_sel_hi:[1,1,0] neg_lo:[1,0,0] neg_hi:[1,0,0]
	s_waitcnt vmcnt(30)
	v_lshlrev_b32_e32 v62, 16, v84
	v_and_b32_e32 v63, 0xffff0000, v84
	v_lshlrev_b32_e32 v18, 16, v85
	v_and_b32_e32 v19, 0xffff0000, v85
	s_waitcnt vmcnt(29)
	v_lshlrev_b32_e32 v64, 16, v88
	v_and_b32_e32 v65, 0xffff0000, v88
	v_sqrt_f32_e32 v70, v1
	v_max_f32_e32 v1, 0, v71
	v_lshlrev_b32_e32 v36, 16, v89
	v_and_b32_e32 v37, 0xffff0000, v89
	v_sqrt_f32_e32 v71, v1
	v_max_f32_e32 v1, 0, v66
	v_pk_mul_f32 v[62:63], v[70:71], v[62:63]
	v_sqrt_f32_e32 v66, v1
	v_max_f32_e32 v1, 0, v67
	v_sqrt_f32_e32 v67, v1
	s_nop 0
	v_pk_mul_f32 v[18:19], v[66:67], v[18:19]
	s_nop 0
	v_pk_mul_f32 v[18:19], v[18:19], v[36:37]
	v_pk_mul_f32 v[36:37], v[62:63], v[64:65]
	v_pk_fma_f32 v[62:63], v[4:5], v[14:15], v[18:19]
	v_pk_fma_f32 v[50:51], v[2:3], v[50:51], v[36:37]
	v_lshlrev_b32_e32 v2, 16, v82
	v_and_b32_e32 v3, 0xffff0000, v82
	v_pk_mul_f32 v[2:3], v[32:33], v[2:3]
	v_lshlrev_b32_e32 v4, 16, v83
	v_mul_f32_e32 v1, 0x3fb8aa3b, v2
	v_exp_f32_e32 v2, v1
	v_mul_f32_e32 v1, 0x3fb8aa3b, v3
	v_exp_f32_e32 v3, v1
	v_and_b32_e32 v5, 0xffff0000, v83
	v_pk_mul_f32 v[4:5], v[30:31], v[4:5]
	v_lshlrev_b32_e32 v14, 16, v86
	v_and_b32_e32 v15, 0xffff0000, v86
	v_lshlrev_b32_e32 v16, 16, v87
	v_and_b32_e32 v17, 0xffff0000, v87
	v_lshlrev_b32_e32 v18, 16, v90
	v_and_b32_e32 v19, 0xffff0000, v90
	v_lshlrev_b32_e32 v20, 16, v91
	v_and_b32_e32 v21, 0xffff0000, v91
	v_mul_f32_e32 v1, 0x3fb8aa3b, v4
	v_exp_f32_e32 v4, v1
	v_mul_f32_e32 v1, 0x3fb8aa3b, v5
	v_pk_fma_f32 v[38:39], v[2:3], v[2:3], 1.0 op_sel_hi:[1,1,0] neg_lo:[1,0,0] neg_hi:[1,0,0]
	v_exp_f32_e32 v5, v1
	v_max_f32_e32 v1, 0, v38
	v_pk_fma_f32 v[36:37], v[4:5], v[4:5], 1.0 op_sel_hi:[1,1,0] neg_lo:[1,0,0] neg_hi:[1,0,0]
	v_sqrt_f32_e32 v38, v1
	v_max_f32_e32 v1, 0, v39
	v_sqrt_f32_e32 v39, v1
	v_max_f32_e32 v1, 0, v36
	v_pk_mul_f32 v[14:15], v[38:39], v[14:15]
	v_pk_mul_f32 v[14:15], v[14:15], v[18:19]
	v_pk_fma_f32 v[64:65], v[6:7], v[2:3], v[14:15]
	s_waitcnt vmcnt(28)
; __device__ __forceinline__ f32x4 unpack4(u32x2 u) { return (f32x4){__uint_as_float(u.x << 16), __uint_as_float(u.x & 0xffff0000u), __uint_as_float(u.y << 16), __uint_as_float(u.y & 0xffff0000u)}; }
; __device__ __forceinline__ u32x2 pack4(f32x4 v) { u32x2 r; r.x = cvt_pk_bf16(v.x, v.y); r.y = cvt_pk_bf16(v.z, v.w); return r; }
; template <int ph>
; __device__ __forceinline__ void run_phase(const Args& args, LAS unsigned char* lds, const int G, const int bx, const bool fin = true) {
;     ...
;             auto lru_ab = [](f32x4 gr, f32x4 gi, f32x4 xc, f32x4 sp, f32x4& a, f32x4& bb) {
;                 const f32x4 la = gr * sp; a = (f32x4){__expf(la[0]), __expf(la[1]), __expf(la[2]), __expf(la[3])};
;                 const f32x4 om = (f32x4){1.f, 1.f, 1.f, 1.f} - a * a;
;                 bb = (f32x4){sqrtf(fmaxf(om[0], 0.f)), sqrtf(fmaxf(om[1], 0.f)), sqrtf(fmaxf(om[2], 0.f)), sqrtf(fmaxf(om[3], 0.f))} * gi * xc; };
;     ...
; #pragma unroll 8
;                 for (int t = 0; t < 32; ++t) { const size_t o = base + (size_t)t * D;
;                     const u32x4 gr = *(const u32x4*)(GR + o), gi = *(const u32x4*)(GI + o), xc = *(const u32x4*)(XC + o), gg = *(const u32x4*)(GG + o);
;                     f32x4 a, bb;
;                     lru_ab(unpack4((u32x2){gr.x, gr.y}), unpack4((u32x2){gi.x, gi.y}), unpack4((u32x2){xc.x, xc.y}), sp0, a, bb); h0 = a * h0 + bb;
;                     lru_ab(unpack4((u32x2){gr.z, gr.w}), unpack4((u32x2){gi.z, gi.w}), unpack4((u32x2){xc.z, xc.w}), sp1, a, bb); h1 = a * h1 + bb;
;                     const u32x2 w0 = pack4(h0 * unpack4((u32x2){gg.x, gg.y})), w1 = pack4(h1 * unpack4((u32x2){gg.z, gg.w}));
;                     *(u32x4*)(LO + o) = (u32x4){w0.x, w0.y, w1.x, w1.y}; }
	v_lshlrev_b32_e32 v2, 16, v92
	v_and_b32_e32 v3, 0xffff0000, v92
	v_pk_mul_f32 v[2:3], v[50:51], v[2:3]
	v_lshlrev_b32_e32 v6, 16, v95
	v_sqrt_f32_e32 v36, v1
	v_max_f32_e32 v1, 0, v37
	v_cvt_pk_bf16_f32 v2, v2, v3
	v_and_b32_e32 v7, 0xffff0000, v95
	v_sqrt_f32_e32 v37, v1
	s_nop 0
	v_pk_mul_f32 v[16:17], v[36:37], v[16:17]
	s_nop 0
	v_pk_mul_f32 v[16:17], v[16:17], v[20:21]
	s_nop 0
	v_pk_fma_f32 v[8:9], v[8:9], v[4:5], v[16:17]
	v_lshlrev_b32_e32 v4, 16, v93
	v_and_b32_e32 v5, 0xffff0000, v93
	v_pk_mul_f32 v[4:5], v[62:63], v[4:5]
	v_pk_mul_f32 v[6:7], v[8:9], v[6:7]
	v_cvt_pk_bf16_f32 v3, v4, v5
	v_lshlrev_b32_e32 v4, 16, v94
	v_and_b32_e32 v5, 0xffff0000, v94
	v_pk_mul_f32 v[4:5], v[64:65], v[4:5]
	s_nop 0
	v_cvt_pk_bf16_f32 v4, v4, v5
	v_cvt_pk_bf16_f32 v5, v6, v7
	global_store_dwordx4 v[212:213], v[2:5], off
	s_nop 0
	s_waitcnt vmcnt(28)
	v_lshlrev_b32_e32 v2, 16, v96
	v_and_b32_e32 v3, 0xffff0000, v96
	v_pk_mul_f32 v[2:3], v[28:29], v[2:3]
	v_lshlrev_b32_e32 v4, 16, v97
	v_mul_f32_e32 v1, 0x3fb8aa3b, v2
	v_exp_f32_e32 v2, v1
	v_mul_f32_e32 v1, 0x3fb8aa3b, v3
	v_exp_f32_e32 v3, v1
	v_and_b32_e32 v5, 0xffff0000, v97
	v_pk_mul_f32 v[4:5], v[26:27], v[4:5]
	v_mul_f32_e32 v1, 0x3fb8aa3b, v4
	v_exp_f32_e32 v4, v1
	v_mul_f32_e32 v1, 0x3fb8aa3b, v5
	v_pk_fma_f32 v[46:47], v[2:3], v[2:3], 1.0 op_sel_hi:[1,1,0] neg_lo:[1,0,0] neg_hi:[1,0,0]
	v_exp_f32_e32 v5, v1
	v_max_f32_e32 v1, 0, v46
	v_pk_fma_f32 v[44:45], v[4:5], v[4:5], 1.0 op_sel_hi:[1,1,0] neg_lo:[1,0,0] neg_hi:[1,0,0]
	s_waitcnt vmcnt(27)
	v_lshlrev_b32_e32 v40, 16, v100
	v_and_b32_e32 v41, 0xffff0000, v100
	v_lshlrev_b32_e32 v14, 16, v101
	v_and_b32_e32 v15, 0xffff0000, v101
	s_waitcnt vmcnt(26)
	v_lshlrev_b32_e32 v42, 16, v104
	v_and_b32_e32 v43, 0xffff0000, v104
	v_sqrt_f32_e32 v46, v1
	v_max_f32_e32 v1, 0, v47
	v_lshlrev_b32_e32 v18, 16, v105
	v_and_b32_e32 v19, 0xffff0000, v105
	v_sqrt_f32_e32 v47, v1
	v_max_f32_e32 v1, 0, v44
	v_pk_mul_f32 v[40:41], v[46:47], v[40:41]
	v_sqrt_f32_e32 v44, v1
	v_max_f32_e32 v1, 0, v45
	v_sqrt_f32_e32 v45, v1
	s_nop 0
	v_pk_mul_f32 v[14:15], v[44:45], v[14:15]
	s_nop 0
	v_pk_mul_f32 v[14:15], v[14:15], v[18:19]
	v_pk_mul_f32 v[18:19], v[40:41], v[42:43]
	v_pk_fma_f32 v[4:5], v[62:63], v[4:5], v[14:15]
	v_lshlrev_b32_e32 v14, 16, v98
	v_and_b32_e32 v15, 0xffff0000, v98
	v_pk_mul_f32 v[14:15], v[32:33], v[14:15]
	v_lshlrev_b32_e32 v6, 16, v99
	v_mul_f32_e32 v1, 0x3fb8aa3b, v14
	v_exp_f32_e32 v14, v1
	v_mul_f32_e32 v1, 0x3fb8aa3b, v15
	v_exp_f32_e32 v15, v1
	v_and_b32_e32 v7, 0xffff0000, v99
	v_pk_mul_f32 v[6:7], v[30:31], v[6:7]
	v_mul_f32_e32 v1, 0x3fb8aa3b, v6
	v_exp_f32_e32 v42, v1
	v_mul_f32_e32 v1, 0x3fb8aa3b, v7
	v_pk_fma_f32 v[44:45], v[14:15], v[14:15], 1.0 op_sel_hi:[1,1,0] neg_lo:[1,0,0] neg_hi:[1,0,0]
	v_exp_f32_e32 v43, v1
	v_max_f32_e32 v1, 0, v44
	v_pk_fma_f32 v[6:7], v[42:43], v[42:43], 1.0 op_sel_hi:[1,1,0] neg_lo:[1,0,0] neg_hi:[1,0,0]
	v_pk_fma_f32 v[2:3], v[50:51], v[2:3], v[18:19]
	v_lshlrev_b32_e32 v18, 16, v102
	v_and_b32_e32 v19, 0xffff0000, v102
	v_lshlrev_b32_e32 v16, 16, v103
	v_and_b32_e32 v17, 0xffff0000, v103
	v_lshlrev_b32_e32 v40, 16, v106
	v_sqrt_f32_e32 v44, v1
	v_max_f32_e32 v1, 0, v45
	v_and_b32_e32 v41, 0xffff0000, v106
	v_lshlrev_b32_e32 v20, 16, v107
	v_and_b32_e32 v21, 0xffff0000, v107
	v_sqrt_f32_e32 v45, v1
	v_max_f32_e32 v1, 0, v6
	v_pk_mul_f32 v[18:19], v[44:45], v[18:19]
	v_sqrt_f32_e32 v6, v1
	v_max_f32_e32 v1, 0, v7
	v_sqrt_f32_e32 v7, v1
	s_nop 0
	v_pk_mul_f32 v[6:7], v[6:7], v[16:17]
	s_nop 0
	v_pk_mul_f32 v[16:17], v[6:7], v[20:21]
	v_pk_mul_f32 v[6:7], v[18:19], v[40:41]
	v_pk_fma_f32 v[8:9], v[8:9], v[42:43], v[16:17]
	v_pk_fma_f32 v[6:7], v[64:65], v[14:15], v[6:7]
	s_waitcnt vmcnt(25)
	v_lshlrev_b32_e32 v14, 16, v108
	v_and_b32_e32 v15, 0xffff0000, v108
	v_lshlrev_b32_e32 v16, 16, v109
	v_and_b32_e32 v17, 0xffff0000, v109
	v_pk_mul_f32 v[16:17], v[4:5], v[16:17]
	v_pk_mul_f32 v[14:15], v[2:3], v[14:15]
	v_lshlrev_b32_e32 v18, 16, v111
	v_cvt_pk_bf16_f32 v14, v14, v15
	v_cvt_pk_bf16_f32 v15, v16, v17
	v_lshlrev_b32_e32 v16, 16, v110
	v_and_b32_e32 v17, 0xffff0000, v110
	v_and_b32_e32 v19, 0xffff0000, v111
	v_pk_mul_f32 v[18:19], v[8:9], v[18:19]
	v_pk_mul_f32 v[16:17], v[6:7], v[16:17]
	v_cvt_pk_bf16_f32 v16, v16, v17
	v_cvt_pk_bf16_f32 v17, v18, v19
	global_store_dwordx4 v[212:213], v[14:17], off offset:2048
	s_nop 1
	s_nop 1
	s_nop 1
	s_nop 1
	s_nop 0
	s_waitcnt vmcnt(25)
	v_lshlrev_b32_e32 v70, 16, v112
	v_and_b32_e32 v71, 0xffff0000, v112
	v_pk_mul_f32 v[70:71], v[28:29], v[70:71]
	v_lshlrev_b32_e32 v38, 16, v113
	v_mul_f32_e32 v1, 0x3fb8aa3b, v70
	v_exp_f32_e32 v70, v1
	v_mul_f32_e32 v1, 0x3fb8aa3b, v71
	v_exp_f32_e32 v71, v1
	v_and_b32_e32 v39, 0xffff0000, v113
	v_pk_mul_f32 v[38:39], v[26:27], v[38:39]
	s_nop 0
	v_mul_f32_e32 v1, 0x3fb8aa3b, v38
	v_exp_f32_e32 v38, v1
	v_mul_f32_e32 v1, 0x3fb8aa3b, v39
	v_pk_fma_f32 v[78:79], v[70:71], v[70:71], 1.0 op_sel_hi:[1,1,0] neg_lo:[1,0,0] neg_hi:[1,0,0]
	v_exp_f32_e32 v39, v1
	v_max_f32_e32 v1, 0, v78
	v_pk_fma_f32 v[76:77], v[38:39], v[38:39], 1.0 op_sel_hi:[1,1,0] neg_lo:[1,0,0] neg_hi:[1,0,0]
	s_waitcnt vmcnt(24)
	v_lshlrev_b32_e32 v72, 16, v116
	v_and_b32_e32 v73, 0xffff0000, v116
	v_lshlrev_b32_e32 v42, 16, v117
	v_and_b32_e32 v43, 0xffff0000, v117
	s_waitcnt vmcnt(23)
; __device__ __forceinline__ f32x4 unpack4(u32x2 u) { return (f32x4){__uint_as_float(u.x << 16), __uint_as_float(u.x & 0xffff0000u), __uint_as_float(u.y << 16), __uint_as_float(u.y & 0xffff0000u)}; }
; __device__ __forceinline__ u32x2 pack4(f32x4 v) { u32x2 r; r.x = cvt_pk_bf16(v.x, v.y); r.y = cvt_pk_bf16(v.z, v.w); return r; }
; template <int ph>
; __device__ __forceinline__ void run_phase(const Args& args, LAS unsigned char* lds, const int G, const int bx, const bool fin = true) {
;     ...
;             auto lru_ab = [](f32x4 gr, f32x4 gi, f32x4 xc, f32x4 sp, f32x4& a, f32x4& bb) {
;                 const f32x4 la = gr * sp; a = (f32x4){__expf(la[0]), __expf(la[1]), __expf(la[2]), __expf(la[3])};
;                 const f32x4 om = (f32x4){1.f, 1.f, 1.f, 1.f} - a * a;
;                 bb = (f32x4){sqrtf(fmaxf(om[0], 0.f)), sqrtf(fmaxf(om[1], 0.f)), sqrtf(fmaxf(om[2], 0.f)), sqrtf(fmaxf(om[3], 0.f))} * gi * xc; };
;     ...
; #pragma unroll 8
;                 for (int t = 0; t < 32; ++t) { const size_t o = base + (size_t)t * D;
;                     const u32x4 gr = *(const u32x4*)(GR + o), gi = *(const u32x4*)(GI + o), xc = *(const u32x4*)(XC + o), gg = *(const u32x4*)(GG + o);
;                     f32x4 a, bb;
;                     lru_ab(unpack4((u32x2){gr.x, gr.y}), unpack4((u32x2){gi.x, gi.y}), unpack4((u32x2){xc.x, xc.y}), sp0, a, bb); h0 = a * h0 + bb;
;                     lru_ab(unpack4((u32x2){gr.z, gr.w}), unpack4((u32x2){gi.z, gi.w}), unpack4((u32x2){xc.z, xc.w}), sp1, a, bb); h1 = a * h1 + bb;
;                     const u32x2 w0 = pack4(h0 * unpack4((u32x2){gg.x, gg.y})), w1 = pack4(h1 * unpack4((u32x2){gg.z, gg.w}));
;                     *(u32x4*)(LO + o) = (u32x4){w0.x, w0.y, w1.x, w1.y}; }
	v_lshlrev_b32_e32 v74, 16, v120
	v_sqrt_f32_e32 v78, v1
	v_max_f32_e32 v1, 0, v79
	v_and_b32_e32 v75, 0xffff0000, v120
	v_lshlrev_b32_e32 v46, 16, v121
	v_and_b32_e32 v47, 0xffff0000, v121
	v_sqrt_f32_e32 v79, v1
	v_max_f32_e32 v1, 0, v76
	v_pk_mul_f32 v[72:73], v[78:79], v[72:73]
	v_sqrt_f32_e32 v76, v1
	v_max_f32_e32 v1, 0, v77
	v_sqrt_f32_e32 v77, v1
	s_nop 0
	v_pk_mul_f32 v[42:43], v[76:77], v[42:43]
	s_nop 0
	v_pk_mul_f32 v[42:43], v[42:43], v[46:47]
	v_pk_mul_f32 v[46:47], v[72:73], v[74:75]
	s_nop 0
	v_pk_fma_f32 v[46:47], v[2:3], v[70:71], v[46:47]
	v_lshlrev_b32_e32 v2, 16, v114
	v_and_b32_e32 v3, 0xffff0000, v114
	v_pk_mul_f32 v[2:3], v[32:33], v[2:3]
	v_pk_fma_f32 v[70:71], v[4:5], v[38:39], v[42:43]
	v_mul_f32_e32 v1, 0x3fb8aa3b, v2
	v_exp_f32_e32 v2, v1
	v_mul_f32_e32 v1, 0x3fb8aa3b, v3
	v_exp_f32_e32 v3, v1
	v_lshlrev_b32_e32 v4, 16, v115
	v_and_b32_e32 v5, 0xffff0000, v115
	v_pk_mul_f32 v[4:5], v[30:31], v[4:5]
	v_mul_f32_e32 v1, 0x3fb8aa3b, v4
	v_exp_f32_e32 v4, v1
	v_mul_f32_e32 v1, 0x3fb8aa3b, v5
	v_pk_fma_f32 v[72:73], v[2:3], v[2:3], 1.0 op_sel_hi:[1,1,0] neg_lo:[1,0,0] neg_hi:[1,0,0]
	v_exp_f32_e32 v5, v1
	v_max_f32_e32 v1, 0, v72
	v_lshlrev_b32_e32 v38, 16, v118
	v_and_b32_e32 v39, 0xffff0000, v118
	v_lshlrev_b32_e32 v40, 16, v119
	v_and_b32_e32 v41, 0xffff0000, v119
	v_lshlrev_b32_e32 v42, 16, v122
	v_and_b32_e32 v43, 0xffff0000, v122
	v_lshlrev_b32_e32 v44, 16, v123
	v_and_b32_e32 v45, 0xffff0000, v123
	v_sqrt_f32_e32 v72, v1
	v_max_f32_e32 v1, 0, v73
	v_pk_fma_f32 v[48:49], v[4:5], v[4:5], 1.0 op_sel_hi:[1,1,0] neg_lo:[1,0,0] neg_hi:[1,0,0]
	v_sqrt_f32_e32 v73, v1
	v_max_f32_e32 v1, 0, v48
	v_pk_mul_f32 v[38:39], v[72:73], v[38:39]
	v_pk_mul_f32 v[38:39], v[38:39], v[42:43]
	v_sqrt_f32_e32 v48, v1
	v_max_f32_e32 v1, 0, v49
	v_sqrt_f32_e32 v49, v1
	s_nop 0
	v_pk_mul_f32 v[40:41], v[48:49], v[40:41]
	s_nop 0
	v_pk_mul_f32 v[40:41], v[40:41], v[44:45]
	v_pk_fma_f32 v[44:45], v[6:7], v[2:3], v[38:39]
	v_pk_fma_f32 v[48:49], v[8:9], v[4:5], v[40:41]
	s_waitcnt vmcnt(22)
	v_lshlrev_b32_e32 v2, 16, v124
	v_and_b32_e32 v3, 0xffff0000, v124
	v_lshlrev_b32_e32 v4, 16, v125
	v_and_b32_e32 v5, 0xffff0000, v125
	v_pk_mul_f32 v[4:5], v[70:71], v[4:5]
	v_pk_mul_f32 v[2:3], v[46:47], v[2:3]
	v_lshlrev_b32_e32 v6, 16, v127
	v_cvt_pk_bf16_f32 v2, v2, v3
	v_cvt_pk_bf16_f32 v3, v4, v5
	v_lshlrev_b32_e32 v4, 16, v126
	v_and_b32_e32 v5, 0xffff0000, v126
	v_and_b32_e32 v7, 0xffff0000, v127
	v_pk_mul_f32 v[6:7], v[48:49], v[6:7]
	v_pk_mul_f32 v[4:5], v[44:45], v[4:5]
	s_nop 0
	v_cvt_pk_bf16_f32 v4, v4, v5
	v_cvt_pk_bf16_f32 v5, v6, v7
	global_store_dwordx4 v[224:225], v[2:5], off offset:-4096
	s_nop 0
	s_waitcnt vmcnt(22)
	v_lshlrev_b32_e32 v50, 16, v128
	v_and_b32_e32 v51, 0xffff0000, v128
	v_pk_mul_f32 v[50:51], v[28:29], v[50:51]
	v_lshlrev_b32_e32 v2, 16, v129
	v_mul_f32_e32 v1, 0x3fb8aa3b, v50
	v_exp_f32_e32 v50, v1
	v_mul_f32_e32 v1, 0x3fb8aa3b, v51
	v_exp_f32_e32 v51, v1
	v_and_b32_e32 v3, 0xffff0000, v129
	v_pk_mul_f32 v[2:3], v[26:27], v[2:3]
	v_mul_f32_e32 v1, 0x3fb8aa3b, v2
	v_exp_f32_e32 v2, v1
	v_mul_f32_e32 v1, 0x3fb8aa3b, v3
	v_pk_fma_f32 v[72:73], v[50:51], v[50:51], 1.0 op_sel_hi:[1,1,0] neg_lo:[1,0,0] neg_hi:[1,0,0]
	v_exp_f32_e32 v3, v1
	v_max_f32_e32 v1, 0, v72
	v_pk_fma_f32 v[66:67], v[2:3], v[2:3], 1.0 op_sel_hi:[1,1,0] neg_lo:[1,0,0] neg_hi:[1,0,0]
	s_waitcnt vmcnt(21)
	v_lshlrev_b32_e32 v62, 16, v132
	v_and_b32_e32 v63, 0xffff0000, v132
	v_lshlrev_b32_e32 v6, 16, v133
	v_and_b32_e32 v7, 0xffff0000, v133
	s_waitcnt vmcnt(20)
	v_lshlrev_b32_e32 v64, 16, v136
	v_and_b32_e32 v65, 0xffff0000, v136
	v_sqrt_f32_e32 v72, v1
	v_max_f32_e32 v1, 0, v73
	v_lshlrev_b32_e32 v36, 16, v137
	v_and_b32_e32 v37, 0xffff0000, v137
	v_sqrt_f32_e32 v73, v1
	v_max_f32_e32 v1, 0, v66
	v_pk_mul_f32 v[62:63], v[72:73], v[62:63]
	v_sqrt_f32_e32 v66, v1
	v_max_f32_e32 v1, 0, v67
	v_sqrt_f32_e32 v67, v1
	s_nop 0
	v_pk_mul_f32 v[6:7], v[66:67], v[6:7]
	s_nop 0
	v_pk_mul_f32 v[6:7], v[6:7], v[36:37]
	v_pk_mul_f32 v[36:37], v[62:63], v[64:65]
	s_nop 0
	v_pk_fma_f32 v[46:47], v[46:47], v[50:51], v[36:37]
	v_pk_fma_f32 v[50:51], v[70:71], v[2:3], v[6:7]
	v_lshlrev_b32_e32 v2, 16, v130
	v_and_b32_e32 v3, 0xffff0000, v130
	v_pk_mul_f32 v[2:3], v[32:33], v[2:3]
	v_lshlrev_b32_e32 v4, 16, v131
	v_mul_f32_e32 v1, 0x3fb8aa3b, v2
	v_exp_f32_e32 v2, v1
	v_mul_f32_e32 v1, 0x3fb8aa3b, v3
	v_exp_f32_e32 v3, v1
	v_and_b32_e32 v5, 0xffff0000, v131
	v_pk_mul_f32 v[4:5], v[30:31], v[4:5]
	v_mul_f32_e32 v1, 0x3fb8aa3b, v4
	v_exp_f32_e32 v4, v1
	v_mul_f32_e32 v1, 0x3fb8aa3b, v5
	v_pk_fma_f32 v[64:65], v[2:3], v[2:3], 1.0 op_sel_hi:[1,1,0] neg_lo:[1,0,0] neg_hi:[1,0,0]
	v_exp_f32_e32 v5, v1
	v_max_f32_e32 v1, 0, v64
	v_pk_fma_f32 v[62:63], v[4:5], v[4:5], 1.0 op_sel_hi:[1,1,0] neg_lo:[1,0,0] neg_hi:[1,0,0]
	v_lshlrev_b32_e32 v6, 16, v134
	v_and_b32_e32 v7, 0xffff0000, v134
	v_lshlrev_b32_e32 v8, 16, v135
	v_and_b32_e32 v9, 0xffff0000, v135
	v_lshlrev_b32_e32 v36, 16, v138
	v_and_b32_e32 v37, 0xffff0000, v138
	v_sqrt_f32_e32 v64, v1
	v_max_f32_e32 v1, 0, v65
	v_lshlrev_b32_e32 v38, 16, v139
	v_and_b32_e32 v39, 0xffff0000, v139
	v_sqrt_f32_e32 v65, v1
	v_max_f32_e32 v1, 0, v62
	v_pk_mul_f32 v[6:7], v[64:65], v[6:7]
	v_pk_mul_f32 v[6:7], v[6:7], v[36:37]
	v_pk_fma_f32 v[44:45], v[44:45], v[2:3], v[6:7]
	s_waitcnt vmcnt(19)
; __device__ __forceinline__ f32x4 unpack4(u32x2 u) { return (f32x4){__uint_as_float(u.x << 16), __uint_as_float(u.x & 0xffff0000u), __uint_as_float(u.y << 16), __uint_as_float(u.y & 0xffff0000u)}; }
; __device__ __forceinline__ u32x2 pack4(f32x4 v) { u32x2 r; r.x = cvt_pk_bf16(v.x, v.y); r.y = cvt_pk_bf16(v.z, v.w); return r; }
; template <int ph>
; __device__ __forceinline__ void run_phase(const Args& args, LAS unsigned char* lds, const int G, const int bx, const bool fin = true) {
;     ...
;             auto lru_ab = [](f32x4 gr, f32x4 gi, f32x4 xc, f32x4 sp, f32x4& a, f32x4& bb) {
;                 const f32x4 la = gr * sp; a = (f32x4){__expf(la[0]), __expf(la[1]), __expf(la[2]), __expf(la[3])};
;                 const f32x4 om = (f32x4){1.f, 1.f, 1.f, 1.f} - a * a;
;                 bb = (f32x4){sqrtf(fmaxf(om[0], 0.f)), sqrtf(fmaxf(om[1], 0.f)), sqrtf(fmaxf(om[2], 0.f)), sqrtf(fmaxf(om[3], 0.f))} * gi * xc; };
;     ...
; #pragma unroll 8
;                 for (int t = 0; t < 32; ++t) { const size_t o = base + (size_t)t * D;
;                     const u32x4 gr = *(const u32x4*)(GR + o), gi = *(const u32x4*)(GI + o), xc = *(const u32x4*)(XC + o), gg = *(const u32x4*)(GG + o);
;                     f32x4 a, bb;
;                     lru_ab(unpack4((u32x2){gr.x, gr.y}), unpack4((u32x2){gi.x, gi.y}), unpack4((u32x2){xc.x, xc.y}), sp0, a, bb); h0 = a * h0 + bb;
;                     lru_ab(unpack4((u32x2){gr.z, gr.w}), unpack4((u32x2){gi.z, gi.w}), unpack4((u32x2){xc.z, xc.w}), sp1, a, bb); h1 = a * h1 + bb;
;                     const u32x2 w0 = pack4(h0 * unpack4((u32x2){gg.x, gg.y})), w1 = pack4(h1 * unpack4((u32x2){gg.z, gg.w}));
;                     *(u32x4*)(LO + o) = (u32x4){w0.x, w0.y, w1.x, w1.y}; }
	v_lshlrev_b32_e32 v2, 16, v140
	v_and_b32_e32 v3, 0xffff0000, v140
	v_pk_mul_f32 v[2:3], v[46:47], v[2:3]
	v_lshlrev_b32_e32 v6, 16, v143
	v_sqrt_f32_e32 v62, v1
	v_max_f32_e32 v1, 0, v63
	v_cvt_pk_bf16_f32 v2, v2, v3
	v_and_b32_e32 v7, 0xffff0000, v143
	v_sqrt_f32_e32 v63, v1
	s_nop 0
	v_pk_mul_f32 v[8:9], v[62:63], v[8:9]
	s_nop 0
	v_pk_mul_f32 v[8:9], v[8:9], v[38:39]
	s_nop 0
	v_pk_fma_f32 v[48:49], v[48:49], v[4:5], v[8:9]
	v_lshlrev_b32_e32 v4, 16, v141
	v_and_b32_e32 v5, 0xffff0000, v141
	v_pk_mul_f32 v[4:5], v[50:51], v[4:5]
	v_pk_mul_f32 v[6:7], v[48:49], v[6:7]
	v_cvt_pk_bf16_f32 v3, v4, v5
	v_lshlrev_b32_e32 v4, 16, v142
	v_and_b32_e32 v5, 0xffff0000, v142
	v_pk_mul_f32 v[4:5], v[44:45], v[4:5]
	s_nop 0
	v_cvt_pk_bf16_f32 v4, v4, v5
	v_cvt_pk_bf16_f32 v5, v6, v7
	global_store_dwordx4 v[222:223], v[2:5], off offset:2048
	s_nop 0
	s_waitcnt vmcnt(19)
	v_lshlrev_b32_e32 v20, 16, v144
	v_and_b32_e32 v21, 0xffff0000, v144
	v_pk_mul_f32 v[20:21], v[28:29], v[20:21]
	v_lshlrev_b32_e32 v2, 16, v145
	v_mul_f32_e32 v1, 0x3fb8aa3b, v20
	v_exp_f32_e32 v20, v1
	v_mul_f32_e32 v1, 0x3fb8aa3b, v21
	v_exp_f32_e32 v21, v1
	v_and_b32_e32 v3, 0xffff0000, v145
	v_pk_mul_f32 v[2:3], v[26:27], v[2:3]
	v_mul_f32_e32 v1, 0x3fb8aa3b, v2
	v_exp_f32_e32 v2, v1
	v_mul_f32_e32 v1, 0x3fb8aa3b, v3
	v_pk_fma_f32 v[70:71], v[20:21], v[20:21], 1.0 op_sel_hi:[1,1,0] neg_lo:[1,0,0] neg_hi:[1,0,0]
	v_exp_f32_e32 v3, v1
	v_max_f32_e32 v1, 0, v70
	v_pk_fma_f32 v[66:67], v[2:3], v[2:3], 1.0 op_sel_hi:[1,1,0] neg_lo:[1,0,0] neg_hi:[1,0,0]
	s_waitcnt vmcnt(18)
	v_lshlrev_b32_e32 v62, 16, v148
	v_and_b32_e32 v63, 0xffff0000, v148
	v_lshlrev_b32_e32 v6, 16, v149
	v_and_b32_e32 v7, 0xffff0000, v149
	s_waitcnt vmcnt(17)
	v_lshlrev_b32_e32 v64, 16, v152
	v_and_b32_e32 v65, 0xffff0000, v152
	v_sqrt_f32_e32 v70, v1
	v_max_f32_e32 v1, 0, v71
	v_lshlrev_b32_e32 v36, 16, v153
	v_and_b32_e32 v37, 0xffff0000, v153
	v_sqrt_f32_e32 v71, v1
	v_max_f32_e32 v1, 0, v66
	v_pk_mul_f32 v[62:63], v[70:71], v[62:63]
	v_sqrt_f32_e32 v66, v1
	v_max_f32_e32 v1, 0, v67
	v_sqrt_f32_e32 v67, v1
	s_nop 0
	v_pk_mul_f32 v[6:7], v[66:67], v[6:7]
	s_nop 0
	v_pk_mul_f32 v[6:7], v[6:7], v[36:37]
	v_pk_mul_f32 v[36:37], v[62:63], v[64:65]
	v_pk_fma_f32 v[50:51], v[50:51], v[2:3], v[6:7]
	v_lshlrev_b32_e32 v2, 16, v146
	v_and_b32_e32 v3, 0xffff0000, v146
	v_pk_mul_f32 v[2:3], v[32:33], v[2:3]
	v_lshlrev_b32_e32 v4, 16, v147
	v_mul_f32_e32 v1, 0x3fb8aa3b, v2
	v_exp_f32_e32 v2, v1
	v_mul_f32_e32 v1, 0x3fb8aa3b, v3
	v_exp_f32_e32 v3, v1
	v_and_b32_e32 v5, 0xffff0000, v147
	v_pk_mul_f32 v[4:5], v[30:31], v[4:5]
	v_mul_f32_e32 v1, 0x3fb8aa3b, v4
	v_exp_f32_e32 v4, v1
	v_mul_f32_e32 v1, 0x3fb8aa3b, v5
	v_pk_fma_f32 v[62:63], v[2:3], v[2:3], 1.0 op_sel_hi:[1,1,0] neg_lo:[1,0,0] neg_hi:[1,0,0]
	v_exp_f32_e32 v5, v1
	v_max_f32_e32 v1, 0, v62
	v_pk_fma_f32 v[46:47], v[46:47], v[20:21], v[36:37]
	v_lshlrev_b32_e32 v20, 16, v154
	v_and_b32_e32 v21, 0xffff0000, v154
	v_lshlrev_b32_e32 v36, 16, v155
	v_and_b32_e32 v37, 0xffff0000, v155
	v_pk_fma_f32 v[38:39], v[4:5], v[4:5], 1.0 op_sel_hi:[1,1,0] neg_lo:[1,0,0] neg_hi:[1,0,0]
	v_lshlrev_b32_e32 v6, 16, v150
	v_sqrt_f32_e32 v62, v1
	v_max_f32_e32 v1, 0, v63
	v_and_b32_e32 v7, 0xffff0000, v150
	v_lshlrev_b32_e32 v8, 16, v151
	v_and_b32_e32 v9, 0xffff0000, v151
	v_sqrt_f32_e32 v63, v1
	v_max_f32_e32 v1, 0, v38
	v_pk_mul_f32 v[6:7], v[62:63], v[6:7]
	v_pk_mul_f32 v[6:7], v[6:7], v[20:21]
	v_pk_fma_f32 v[44:45], v[44:45], v[2:3], v[6:7]
	s_waitcnt vmcnt(16)
	v_lshlrev_b32_e32 v2, 16, v156
	v_and_b32_e32 v3, 0xffff0000, v156
	v_pk_mul_f32 v[2:3], v[46:47], v[2:3]
	v_lshlrev_b32_e32 v6, 16, v159
	v_sqrt_f32_e32 v38, v1
	v_max_f32_e32 v1, 0, v39
	v_cvt_pk_bf16_f32 v2, v2, v3
	v_and_b32_e32 v7, 0xffff0000, v159
	v_sqrt_f32_e32 v39, v1
	s_nop 0
	v_pk_mul_f32 v[8:9], v[38:39], v[8:9]
	s_nop 0
	v_pk_mul_f32 v[8:9], v[8:9], v[36:37]
	s_nop 0
	v_pk_fma_f32 v[8:9], v[48:49], v[4:5], v[8:9]
	v_lshlrev_b32_e32 v4, 16, v157
	v_and_b32_e32 v5, 0xffff0000, v157
	v_pk_mul_f32 v[4:5], v[50:51], v[4:5]
	v_pk_mul_f32 v[6:7], v[8:9], v[6:7]
	v_cvt_pk_bf16_f32 v3, v4, v5
	v_lshlrev_b32_e32 v4, 16, v158
	v_and_b32_e32 v5, 0xffff0000, v158
	v_pk_mul_f32 v[4:5], v[44:45], v[4:5]
	s_nop 0
	v_cvt_pk_bf16_f32 v4, v4, v5
	v_cvt_pk_bf16_f32 v5, v6, v7
	global_store_dwordx4 v[224:225], v[2:5], off
	s_nop 0
	s_nop 0
	s_nop 0
	s_waitcnt vmcnt(16)
	v_lshlrev_b32_e32 v2, 16, v160
	v_and_b32_e32 v3, 0xffff0000, v160
	v_pk_mul_f32 v[2:3], v[28:29], v[2:3]
	v_lshlrev_b32_e32 v4, 16, v161
	v_mul_f32_e32 v1, 0x3fb8aa3b, v2
	v_exp_f32_e32 v2, v1
	v_mul_f32_e32 v1, 0x3fb8aa3b, v3
	v_exp_f32_e32 v3, v1
	v_and_b32_e32 v5, 0xffff0000, v161
	v_pk_mul_f32 v[4:5], v[26:27], v[4:5]
	v_mul_f32_e32 v1, 0x3fb8aa3b, v4
	v_exp_f32_e32 v4, v1
	v_mul_f32_e32 v1, 0x3fb8aa3b, v5
	v_pk_fma_f32 v[62:63], v[2:3], v[2:3], 1.0 op_sel_hi:[1,1,0] neg_lo:[1,0,0] neg_hi:[1,0,0]
	v_exp_f32_e32 v5, v1
	v_max_f32_e32 v1, 0, v62
	v_pk_fma_f32 v[48:49], v[4:5], v[4:5], 1.0 op_sel_hi:[1,1,0] neg_lo:[1,0,0] neg_hi:[1,0,0]
	s_waitcnt vmcnt(15)
	v_lshlrev_b32_e32 v40, 16, v164
	v_and_b32_e32 v41, 0xffff0000, v164
	v_lshlrev_b32_e32 v36, 16, v165
	v_and_b32_e32 v37, 0xffff0000, v165
	s_waitcnt vmcnt(14)
; __device__ __forceinline__ f32x4 unpack4(u32x2 u) { return (f32x4){__uint_as_float(u.x << 16), __uint_as_float(u.x & 0xffff0000u), __uint_as_float(u.y << 16), __uint_as_float(u.y & 0xffff0000u)}; }
; __device__ __forceinline__ u32x2 pack4(f32x4 v) { u32x2 r; r.x = cvt_pk_bf16(v.x, v.y); r.y = cvt_pk_bf16(v.z, v.w); return r; }
; template <int ph>
; __device__ __forceinline__ void run_phase(const Args& args, LAS unsigned char* lds, const int G, const int bx, const bool fin = true) {
;     ...
;             auto lru_ab = [](f32x4 gr, f32x4 gi, f32x4 xc, f32x4 sp, f32x4& a, f32x4& bb) {
;                 const f32x4 la = gr * sp; a = (f32x4){__expf(la[0]), __expf(la[1]), __expf(la[2]), __expf(la[3])};
;                 const f32x4 om = (f32x4){1.f, 1.f, 1.f, 1.f} - a * a;
;                 bb = (f32x4){sqrtf(fmaxf(om[0], 0.f)), sqrtf(fmaxf(om[1], 0.f)), sqrtf(fmaxf(om[2], 0.f)), sqrtf(fmaxf(om[3], 0.f))} * gi * xc; };
;     ...
; #pragma unroll 8
;                 for (int t = 0; t < 32; ++t) { const size_t o = base + (size_t)t * D;
;                     const u32x4 gr = *(const u32x4*)(GR + o), gi = *(const u32x4*)(GI + o), xc = *(const u32x4*)(XC + o), gg = *(const u32x4*)(GG + o);
;                     f32x4 a, bb;
;                     lru_ab(unpack4((u32x2){gr.x, gr.y}), unpack4((u32x2){gi.x, gi.y}), unpack4((u32x2){xc.x, xc.y}), sp0, a, bb); h0 = a * h0 + bb;
;                     lru_ab(unpack4((u32x2){gr.z, gr.w}), unpack4((u32x2){gi.z, gi.w}), unpack4((u32x2){xc.z, xc.w}), sp1, a, bb); h1 = a * h1 + bb;
;                     const u32x2 w0 = pack4(h0 * unpack4((u32x2){gg.x, gg.y})), w1 = pack4(h1 * unpack4((u32x2){gg.z, gg.w}));
;                     *(u32x4*)(LO + o) = (u32x4){w0.x, w0.y, w1.x, w1.y}; }
	v_lshlrev_b32_e32 v42, 16, v168
	v_and_b32_e32 v43, 0xffff0000, v168
	v_sqrt_f32_e32 v62, v1
	v_max_f32_e32 v1, 0, v63
	v_lshlrev_b32_e32 v14, 16, v169
	v_and_b32_e32 v15, 0xffff0000, v169
	v_sqrt_f32_e32 v63, v1
	v_max_f32_e32 v1, 0, v48
	v_pk_mul_f32 v[40:41], v[62:63], v[40:41]
	v_sqrt_f32_e32 v48, v1
	v_max_f32_e32 v1, 0, v49
	v_sqrt_f32_e32 v49, v1
	s_nop 0
	v_pk_mul_f32 v[36:37], v[48:49], v[36:37]
	s_nop 0
	v_pk_mul_f32 v[14:15], v[36:37], v[14:15]
	v_pk_mul_f32 v[36:37], v[40:41], v[42:43]
	v_pk_fma_f32 v[4:5], v[50:51], v[4:5], v[14:15]
	v_lshlrev_b32_e32 v14, 16, v162
	v_and_b32_e32 v15, 0xffff0000, v162
	v_pk_mul_f32 v[14:15], v[32:33], v[14:15]
	v_lshlrev_b32_e32 v6, 16, v163
	v_mul_f32_e32 v1, 0x3fb8aa3b, v14
	v_exp_f32_e32 v14, v1
	v_mul_f32_e32 v1, 0x3fb8aa3b, v15
	v_exp_f32_e32 v15, v1
	v_and_b32_e32 v7, 0xffff0000, v163
	v_pk_mul_f32 v[6:7], v[30:31], v[6:7]
	v_pk_fma_f32 v[2:3], v[46:47], v[2:3], v[36:37]
	v_mul_f32_e32 v1, 0x3fb8aa3b, v6
	v_exp_f32_e32 v42, v1
	v_mul_f32_e32 v1, 0x3fb8aa3b, v7
	v_pk_fma_f32 v[46:47], v[14:15], v[14:15], 1.0 op_sel_hi:[1,1,0] neg_lo:[1,0,0] neg_hi:[1,0,0]
	v_exp_f32_e32 v43, v1
	v_max_f32_e32 v1, 0, v46
	v_pk_fma_f32 v[6:7], v[42:43], v[42:43], 1.0 op_sel_hi:[1,1,0] neg_lo:[1,0,0] neg_hi:[1,0,0]
	v_lshlrev_b32_e32 v36, 16, v166
	v_and_b32_e32 v37, 0xffff0000, v166
	v_lshlrev_b32_e32 v38, 16, v167
	v_and_b32_e32 v39, 0xffff0000, v167
	v_lshlrev_b32_e32 v40, 16, v170
	v_and_b32_e32 v41, 0xffff0000, v170
	v_sqrt_f32_e32 v46, v1
	v_max_f32_e32 v1, 0, v47
	v_lshlrev_b32_e32 v16, 16, v171
	v_and_b32_e32 v17, 0xffff0000, v171
	v_sqrt_f32_e32 v47, v1
	v_max_f32_e32 v1, 0, v6
	v_pk_mul_f32 v[36:37], v[46:47], v[36:37]
	v_sqrt_f32_e32 v6, v1
	v_max_f32_e32 v1, 0, v7
	v_sqrt_f32_e32 v7, v1
	s_nop 0
	v_pk_mul_f32 v[6:7], v[6:7], v[38:39]
	s_nop 0
	v_pk_mul_f32 v[16:17], v[6:7], v[16:17]
	v_pk_mul_f32 v[6:7], v[36:37], v[40:41]
	v_pk_fma_f32 v[8:9], v[8:9], v[42:43], v[16:17]
	v_pk_fma_f32 v[6:7], v[44:45], v[14:15], v[6:7]
	s_waitcnt vmcnt(13)
	v_lshlrev_b32_e32 v14, 16, v172
	v_and_b32_e32 v15, 0xffff0000, v172
	v_lshlrev_b32_e32 v16, 16, v173
	v_and_b32_e32 v17, 0xffff0000, v173
	v_pk_mul_f32 v[16:17], v[4:5], v[16:17]
	v_pk_mul_f32 v[14:15], v[2:3], v[14:15]
	v_lshlrev_b32_e32 v18, 16, v175
	v_cvt_pk_bf16_f32 v14, v14, v15
	v_cvt_pk_bf16_f32 v15, v16, v17
	v_lshlrev_b32_e32 v16, 16, v174
	v_and_b32_e32 v17, 0xffff0000, v174
	v_and_b32_e32 v19, 0xffff0000, v175
	v_pk_mul_f32 v[18:19], v[8:9], v[18:19]
	v_pk_mul_f32 v[16:17], v[6:7], v[16:17]
	s_nop 0
	v_cvt_pk_bf16_f32 v16, v16, v17
	v_cvt_pk_bf16_f32 v17, v18, v19
	global_store_dwordx4 v[224:225], v[14:17], off offset:2048
	s_nop 1
	s_nop 1
	s_nop 0
	s_waitcnt vmcnt(12)
	v_lshlrev_b32_e32 v40, 16, v180
	v_lshlrev_b32_e32 v38, 16, v176
	v_and_b32_e32 v39, 0xffff0000, v176
	v_pk_mul_f32 v[38:39], v[28:29], v[38:39]
	v_lshlrev_b32_e32 v14, 16, v177
	v_mul_f32_e32 v1, 0x3fb8aa3b, v38
	v_exp_f32_e32 v38, v1
	v_mul_f32_e32 v1, 0x3fb8aa3b, v39
	v_exp_f32_e32 v39, v1
	v_and_b32_e32 v15, 0xffff0000, v177
	v_pk_mul_f32 v[14:15], v[26:27], v[14:15]
	v_mul_f32_e32 v1, 0x3fb8aa3b, v14
	v_exp_f32_e32 v14, v1
	v_mul_f32_e32 v1, 0x3fb8aa3b, v15
	v_pk_fma_f32 v[66:67], v[38:39], v[38:39], 1.0 op_sel_hi:[1,1,0] neg_lo:[1,0,0] neg_hi:[1,0,0]
	v_exp_f32_e32 v15, v1
	v_max_f32_e32 v1, 0, v66
	v_pk_fma_f32 v[64:65], v[14:15], v[14:15], 1.0 op_sel_hi:[1,1,0] neg_lo:[1,0,0] neg_hi:[1,0,0]
	v_and_b32_e32 v41, 0xffff0000, v180
	v_lshlrev_b32_e32 v18, 16, v181
	v_and_b32_e32 v19, 0xffff0000, v181
	s_waitcnt vmcnt(11)
	v_lshlrev_b32_e32 v62, 16, v184
	v_and_b32_e32 v63, 0xffff0000, v184
	v_lshlrev_b32_e32 v44, 16, v185
	v_sqrt_f32_e32 v66, v1
	v_max_f32_e32 v1, 0, v67
	v_and_b32_e32 v45, 0xffff0000, v185
	v_sqrt_f32_e32 v67, v1
	v_max_f32_e32 v1, 0, v64
	v_pk_mul_f32 v[40:41], v[66:67], v[40:41]
	v_pk_mul_f32 v[40:41], v[40:41], v[62:63]
	v_pk_fma_f32 v[2:3], v[2:3], v[38:39], v[40:41]
	v_lshlrev_b32_e32 v38, 16, v187
	v_and_b32_e32 v39, 0xffff0000, v187
	v_sqrt_f32_e32 v64, v1
	v_max_f32_e32 v1, 0, v65
	v_sqrt_f32_e32 v65, v1
	s_nop 0
	v_pk_mul_f32 v[18:19], v[64:65], v[18:19]
	s_nop 0
	v_pk_mul_f32 v[18:19], v[18:19], v[44:45]
	s_nop 0
	v_pk_fma_f32 v[40:41], v[4:5], v[14:15], v[18:19]
	v_lshlrev_b32_e32 v4, 16, v178
	v_and_b32_e32 v5, 0xffff0000, v178
	v_pk_mul_f32 v[4:5], v[32:33], v[4:5]
	v_lshlrev_b32_e32 v14, 16, v179
	v_mul_f32_e32 v1, 0x3fb8aa3b, v4
	v_exp_f32_e32 v4, v1
	v_mul_f32_e32 v1, 0x3fb8aa3b, v5
	v_exp_f32_e32 v5, v1
	v_and_b32_e32 v15, 0xffff0000, v179
	v_pk_mul_f32 v[14:15], v[30:31], v[14:15]
	v_lshlrev_b32_e32 v16, 16, v182
	v_and_b32_e32 v17, 0xffff0000, v182
	v_lshlrev_b32_e32 v18, 16, v183
	v_and_b32_e32 v19, 0xffff0000, v183
	v_lshlrev_b32_e32 v20, 16, v186
	v_and_b32_e32 v21, 0xffff0000, v186
	v_mul_f32_e32 v1, 0x3fb8aa3b, v14
	v_exp_f32_e32 v14, v1
	v_mul_f32_e32 v1, 0x3fb8aa3b, v15
	v_pk_fma_f32 v[46:47], v[4:5], v[4:5], 1.0 op_sel_hi:[1,1,0] neg_lo:[1,0,0] neg_hi:[1,0,0]
	v_exp_f32_e32 v15, v1
	v_max_f32_e32 v1, 0, v46
	v_pk_fma_f32 v[44:45], v[14:15], v[14:15], 1.0 op_sel_hi:[1,1,0] neg_lo:[1,0,0] neg_hi:[1,0,0]
	v_sqrt_f32_e32 v46, v1
	v_max_f32_e32 v1, 0, v47
	v_sqrt_f32_e32 v47, v1
	v_max_f32_e32 v1, 0, v44
	v_pk_mul_f32 v[16:17], v[46:47], v[16:17]
	v_pk_mul_f32 v[16:17], v[16:17], v[20:21]
	v_sqrt_f32_e32 v44, v1
	v_max_f32_e32 v1, 0, v45
	v_sqrt_f32_e32 v45, v1
	s_nop 0
	v_pk_mul_f32 v[18:19], v[44:45], v[18:19]
	s_nop 0
	v_pk_mul_f32 v[18:19], v[18:19], v[38:39]
	v_pk_fma_f32 v[38:39], v[6:7], v[4:5], v[16:17]
	s_waitcnt vmcnt(10)
; __device__ __forceinline__ f32x4 unpack4(u32x2 u) { return (f32x4){__uint_as_float(u.x << 16), __uint_as_float(u.x & 0xffff0000u), __uint_as_float(u.y << 16), __uint_as_float(u.y & 0xffff0000u)}; }
; __device__ __forceinline__ u32x2 pack4(f32x4 v) { u32x2 r; r.x = cvt_pk_bf16(v.x, v.y); r.y = cvt_pk_bf16(v.z, v.w); return r; }
; template <int ph>
; __device__ __forceinline__ void run_phase(const Args& args, LAS unsigned char* lds, const int G, const int bx, const bool fin = true) {
;     ...
; #pragma unroll 8
;                 for (int t = 0; t < 32; ++t) { const size_t o = base + (size_t)t * D;
;                     const u32x4 gr = *(const u32x4*)(GR + o), gi = *(const u32x4*)(GI + o), xc = *(const u32x4*)(XC + o), gg = *(const u32x4*)(GG + o);
;                     f32x4 a, bb;
;                     lru_ab(unpack4((u32x2){gr.x, gr.y}), unpack4((u32x2){gi.x, gi.y}), unpack4((u32x2){xc.x, xc.y}), sp0, a, bb); h0 = a * h0 + bb;
;                     lru_ab(unpack4((u32x2){gr.z, gr.w}), unpack4((u32x2){gi.z, gi.w}), unpack4((u32x2){xc.z, xc.w}), sp1, a, bb); h1 = a * h1 + bb;
;                     const u32x2 w0 = pack4(h0 * unpack4((u32x2){gg.x, gg.y})), w1 = pack4(h1 * unpack4((u32x2){gg.z, gg.w}));
;                     *(u32x4*)(LO + o) = (u32x4){w0.x, w0.y, w1.x, w1.y}; }
;                 if (seg == 63) { *(f32x4*)(out + O_PLRU + (size_t)b * D + ch) = h0; *(f32x4*)(out + O_PLRU + (size_t)b * D + ch + 4) = h1; }
	v_lshlrev_b32_e32 v4, 16, v188
	v_and_b32_e32 v5, 0xffff0000, v188
	v_lshlrev_b32_e32 v6, 16, v189
	v_and_b32_e32 v7, 0xffff0000, v189
	v_pk_mul_f32 v[6:7], v[40:41], v[6:7]
	v_pk_mul_f32 v[4:5], v[2:3], v[4:5]
	v_pk_fma_f32 v[8:9], v[8:9], v[14:15], v[18:19]
	v_cvt_pk_bf16_f32 v4, v4, v5
	v_cvt_pk_bf16_f32 v5, v6, v7
	v_lshlrev_b32_e32 v6, 16, v190
	v_and_b32_e32 v7, 0xffff0000, v190
	v_lshlrev_b32_e32 v14, 16, v191
	v_and_b32_e32 v15, 0xffff0000, v191
	v_pk_mul_f32 v[14:15], v[8:9], v[14:15]
	v_pk_mul_f32 v[6:7], v[38:39], v[6:7]
	s_nop 0
	v_cvt_pk_bf16_f32 v6, v6, v7
	v_cvt_pk_bf16_f32 v7, v14, v15
	global_store_dwordx4 v[238:239], v[4:7], off
	s_nop 0
	s_nop 0
	s_waitcnt vmcnt(10)
	v_lshlrev_b32_e32 v42, 16, v192
	v_and_b32_e32 v43, 0xffff0000, v192
	v_pk_mul_f32 v[42:43], v[28:29], v[42:43]
	v_lshlrev_b32_e32 v18, 16, v193
	v_mul_f32_e32 v1, 0x3fb8aa3b, v42
	v_exp_f32_e32 v42, v1
	v_mul_f32_e32 v1, 0x3fb8aa3b, v43
	v_exp_f32_e32 v43, v1
	v_and_b32_e32 v19, 0xffff0000, v193
	v_pk_mul_f32 v[18:19], v[26:27], v[18:19]
	v_mul_f32_e32 v1, 0x3fb8aa3b, v18
	v_exp_f32_e32 v18, v1
	v_mul_f32_e32 v1, 0x3fb8aa3b, v19
	v_pk_fma_f32 v[50:51], v[42:43], v[42:43], 1.0 op_sel_hi:[1,1,0] neg_lo:[1,0,0] neg_hi:[1,0,0]
	v_exp_f32_e32 v19, v1
	v_max_f32_e32 v1, 0, v50
	v_pk_fma_f32 v[48:49], v[18:19], v[18:19], 1.0 op_sel_hi:[1,1,0] neg_lo:[1,0,0] neg_hi:[1,0,0]
	s_waitcnt vmcnt(9)
	v_lshlrev_b32_e32 v44, 16, v196
	v_and_b32_e32 v45, 0xffff0000, v196
	v_lshlrev_b32_e32 v14, 16, v197
	v_and_b32_e32 v15, 0xffff0000, v197
	s_waitcnt vmcnt(8)
	v_lshlrev_b32_e32 v46, 16, v204
	v_and_b32_e32 v47, 0xffff0000, v204
	v_sqrt_f32_e32 v50, v1
	v_max_f32_e32 v1, 0, v51
	v_lshlrev_b32_e32 v4, 16, v205
	v_and_b32_e32 v5, 0xffff0000, v205
	v_sqrt_f32_e32 v51, v1
	v_max_f32_e32 v1, 0, v48
	v_pk_mul_f32 v[44:45], v[50:51], v[44:45]
	v_pk_mul_f32 v[44:45], v[44:45], v[46:47]
	v_pk_fma_f32 v[2:3], v[2:3], v[42:43], v[44:45]
	v_sqrt_f32_e32 v48, v1
	v_max_f32_e32 v1, 0, v49
	v_sqrt_f32_e32 v49, v1
	s_nop 0
	v_pk_mul_f32 v[14:15], v[48:49], v[14:15]
	s_nop 0
	v_pk_mul_f32 v[4:5], v[14:15], v[4:5]
	v_lshlrev_b32_e32 v14, 16, v194
	v_and_b32_e32 v15, 0xffff0000, v194
	v_pk_mul_f32 v[14:15], v[32:33], v[14:15]
	v_pk_fma_f32 v[4:5], v[40:41], v[18:19], v[4:5]
	v_mul_f32_e32 v1, 0x3fb8aa3b, v14
	v_exp_f32_e32 v14, v1
	v_mul_f32_e32 v1, 0x3fb8aa3b, v15
	v_exp_f32_e32 v15, v1
	v_lshlrev_b32_e32 v18, 16, v195
	v_and_b32_e32 v19, 0xffff0000, v195
	v_pk_mul_f32 v[18:19], v[30:31], v[18:19]
	v_mul_f32_e32 v1, 0x3fb8aa3b, v18
	v_exp_f32_e32 v18, v1
	v_mul_f32_e32 v1, 0x3fb8aa3b, v19
	v_pk_fma_f32 v[44:45], v[14:15], v[14:15], 1.0 op_sel_hi:[1,1,0] neg_lo:[1,0,0] neg_hi:[1,0,0]
	v_exp_f32_e32 v19, v1
	v_max_f32_e32 v1, 0, v44
	v_pk_fma_f32 v[42:43], v[18:19], v[18:19], 1.0 op_sel_hi:[1,1,0] neg_lo:[1,0,0] neg_hi:[1,0,0]
	v_lshlrev_b32_e32 v20, 16, v198
	v_and_b32_e32 v21, 0xffff0000, v198
	v_lshlrev_b32_e32 v16, 16, v199
	v_and_b32_e32 v17, 0xffff0000, v199
	v_lshlrev_b32_e32 v40, 16, v206
	v_and_b32_e32 v41, 0xffff0000, v206
	v_sqrt_f32_e32 v44, v1
	v_max_f32_e32 v1, 0, v45
	v_lshlrev_b32_e32 v6, 16, v207
	v_and_b32_e32 v7, 0xffff0000, v207
	v_sqrt_f32_e32 v45, v1
	v_max_f32_e32 v1, 0, v42
	v_pk_mul_f32 v[20:21], v[44:45], v[20:21]
	v_pk_mul_f32 v[20:21], v[20:21], v[40:41]
	v_sqrt_f32_e32 v42, v1
	v_max_f32_e32 v1, 0, v43
	v_sqrt_f32_e32 v43, v1
	s_nop 0
	v_pk_mul_f32 v[16:17], v[42:43], v[16:17]
	s_nop 0
	v_pk_mul_f32 v[6:7], v[16:17], v[6:7]
	s_nop 0
	v_pk_fma_f32 v[8:9], v[8:9], v[18:19], v[6:7]
	v_pk_fma_f32 v[6:7], v[38:39], v[14:15], v[20:21]
	s_waitcnt vmcnt(7)
	v_lshlrev_b32_e32 v14, 16, v208
	v_and_b32_e32 v15, 0xffff0000, v208
	v_lshlrev_b32_e32 v10, 16, v209
	v_and_b32_e32 v11, 0xffff0000, v209
	v_pk_mul_f32 v[16:17], v[4:5], v[10:11]
	v_pk_mul_f32 v[10:11], v[2:3], v[14:15]
	v_lshlrev_b32_e32 v14, 16, v210
	v_and_b32_e32 v15, 0xffff0000, v210
	v_lshlrev_b32_e32 v12, 16, v211
	v_and_b32_e32 v13, 0xffff0000, v211
	v_cvt_pk_bf16_f32 v10, v10, v11
	v_cvt_pk_bf16_f32 v11, v16, v17
	v_pk_mul_f32 v[16:17], v[8:9], v[12:13]
	v_pk_mul_f32 v[12:13], v[6:7], v[14:15]
	s_nop 0
	v_cvt_pk_bf16_f32 v12, v12, v13
	v_cvt_pk_bf16_f32 v13, v16, v17
	global_store_dwordx4 v[238:239], v[10:13], off offset:2048
	s_cbranch_scc0 .LBB0_1073
	s_and_saveexec_b64 s[0:1], s[4:5]
	s_cbranch_execz .LBB0_1043
	s_lshl_b64 s[10:11], s[22:23], 12
	s_add_u32 s10, s59, s10
	s_addc_u32 s11, s60, s11
	global_store_dwordx4 v60, v[2:5], s[10:11]
	global_store_dwordx4 v60, v[6:9], s[10:11] offset:16
	s_branch .LBB0_1043
